# baseline (speedup 1.0000x reference)
;     DI size_t aoff(const Unit& u, size_t tstep) const { return (size_t)u.pm * tstep; }
;     DI size_t boff(const Unit& u, size_t tstep) const { return (size_t)u.pn * tstep; }
;     DI bool next(int i, Unit& u) const { const long L = (long)i * G + c; if (L >= np) return false; u.pm = pmv; u.pn = (int)(L % nN); u.ks = (int)(L / nN); return true; }
;     DI size_t aoff(const Unit& u, size_t) const { return (size_t)u.ks * kbytes; }
;     DI size_t boff(const Unit& u, size_t tstep) const { return (size_t)u.pn * tstep + (size_t)u.ks * kbytes; }
;     DI bool next(int i, Unit& u) const { Unit t; if (!S.next(i / 3, t)) return false; u.pm = t.pm; u.pn = t.pn; u.ks = i % 3; return true; }
;     DI size_t aoff(const Unit& u, size_t tstep) const { return (u.ks < 2 ? offU : offOA) + (size_t)u.pm * tstep; }
; #define PG8_WAIT_V(n) asm volatile("s_waitcnt vmcnt(" #n ")" ::: "memory")
; template <class Epi, class Sched>
; DI void gemm_phase(LAS unsigned char* lds, const Gemm g, const Sched& S, const Epi& E) {
;     ...
;     for (;;) {
;         const bool has_next = S.next(ui + 1, nxt);
;         const char* nA = has_next ? (const char*)g.A + S.aoff(nxt, tstep) : cA; const char* nB = has_next ? (const char*)g.Bt + S.boff(nxt, tstep) : cB;
;         for (int t = 0; t < nt; t += 2) {
;             if constexpr (Epi::HAS_MID) { if (t == E.mid_t(nt)) { int fr3 = fr, fq3 = fq; asm volatile("" : "+v"(fr3), "+v"(fq3)); E.mid(acc, cur, wr, wc, fr3, fq3); } }
;             const bool last = (t == nt - 2);
;             const char* a1 = cA + (size_t)(t + 1) * kstep;
;             const char* a2 = last ? nA : cA + (size_t)(t + 2) * kstep; const char* b2 = last ? nB : cB + (size_t)(t + 2) * kstep;
;             const char* a3 = a2 + kstep; const char* b3 = b2 + kstep;
;             PG8_LDB(B0, 0, 0); PG8_SCHED; PG8_LDA(At, 0, 0); PG8_STAGE(PG8_SA(1, 1), a1 + hstep, voffA);
;             PG8_WAIT_L(8); PG8_BAR; PG8_WAIT_L(0); PG8_MMA(0, 0, At, B0); PG8_BAR; PG8_SCHED;
;             PG8_LDB(B1, 0, 1); PG8_STAGE(PG8_SB(0, 0), b2, voffB);
;             PG8_BAR; PG8_WAIT_L(0); PG8_MMA(0, 1, At, B1); PG8_BAR;
;             PG8_LDA(At, 0, 1); PG8_STAGE(PG8_SA(0, 0), a2, voffA);
;             PG8_BAR; PG8_WAIT_L(0); PG8_MMA(1, 0, At, B0); PG8_BAR; PG8_SCHED;
;             PG8_STAGE(PG8_SB(0, 1), b2 + hstep, voffB);
;             PG8_WAIT_V(6); PG8_BAR; PG8_MMA(1, 1, At, B1); PG8_BAR;
.LBB0_218:
	s_ashr_i32 s17, s16, 31
	s_lshl_b64 s[0:1], s[16:17], 20
	v_cmp_lt_i64_e32 vcc, s[18:19], v[140:141]
	s_add_u32 s18, s47, s0
	s_addc_u32 s19, s48, s1
	s_and_b64 s[0:1], vcc, exec
	s_cselect_b32 s17, s19, s41
	s_cselect_b32 s65, s18, s40
	s_ashr_i32 s15, s14, 31
	s_lshl_b64 s[0:1], s[14:15], 20
	s_add_u32 s36, s49, s0
	s_addc_u32 s37, s50, s1
	s_and_b64 s[0:1], vcc, exec
	s_cselect_b32 s15, s37, s43
	s_cselect_b32 s66, s36, s42
	s_add_u32 s40, s40, 0x80080
	s_addc_u32 s41, s41, 0
	s_add_u32 s67, s42, 0x100
	v_mov_b32_e32 v0, 0
	s_addc_u32 s68, s43, 0
	s_mov_b32 s69, -2
	ds_read_b128 v[150:153], v147
	ds_read_b128 v[154:157], v147 offset:1024
	ds_read_b128 v[162:165], v147 offset:2048
	ds_read_b128 v[166:169], v147 offset:3072
	s_add_u32 s0, s40, 0xfff80080
	s_addc_u32 s1, s41, -1
	s_cmp_eq_u32 s69, 28
	s_cselect_b32 s45, s17, s1
	s_cselect_b32 s44, s65, s0
	s_cselect_b32 s43, s15, s68
	s_cselect_b32 s42, s66, s67
	s_add_i32 m0, s39, 0xc000
	ds_read_b128 v[170:173], v148
	ds_read_b128 v[174:177], v148 offset:1024
	ds_read_b128 v[178:181], v148 offset:2048
	ds_read_b128 v[188:191], v148 offset:3072
	ds_read_b128 v[194:197], v148 offset:4096
	ds_read_b128 v[198:201], v148 offset:5120
	ds_read_b128 v[202:205], v148 offset:6144
	global_load_lds_dwordx4 v136, s[40:41]
	s_add_i32 m0, s39, 0xe000
	ds_read_b128 v[206:209], v148 offset:7168
	global_load_lds_dwordx4 v138, s[40:41]
	s_waitcnt lgkmcnt(8)
	s_barrier
	s_waitcnt lgkmcnt(0)
	s_setprio 1
	v_mfma_f32_16x16x32_bf16 v[124:127], v[150:153], v[170:173], 0
	v_mfma_f32_16x16x32_bf16 v[120:123], v[162:165], v[170:173], 0
	v_mfma_f32_16x16x32_bf16 v[108:111], v[150:153], v[178:181], 0
	v_mfma_f32_16x16x32_bf16 v[104:107], v[162:165], v[178:181], 0
	v_mfma_f32_16x16x32_bf16 v[92:95], v[150:153], v[194:197], 0
	v_mfma_f32_16x16x32_bf16 v[88:91], v[162:165], v[194:197], 0
	v_mfma_f32_16x16x32_bf16 v[76:79], v[150:153], v[202:205], 0
	v_mfma_f32_16x16x32_bf16 v[72:75], v[162:165], v[202:205], 0
	v_mfma_f32_16x16x32_bf16 v[124:127], v[154:157], v[174:177], v[124:127]
	v_mfma_f32_16x16x32_bf16 v[120:123], v[166:169], v[174:177], v[120:123]
	v_mfma_f32_16x16x32_bf16 v[108:111], v[154:157], v[188:191], v[108:111]
	v_mfma_f32_16x16x32_bf16 v[104:107], v[166:169], v[188:191], v[104:107]
	v_mfma_f32_16x16x32_bf16 v[92:95], v[154:157], v[198:201], v[92:95]
	v_mfma_f32_16x16x32_bf16 v[88:91], v[166:169], v[198:201], v[88:91]
	v_mfma_f32_16x16x32_bf16 v[76:79], v[154:157], v[206:209], v[76:79]
	v_mfma_f32_16x16x32_bf16 v[72:75], v[166:169], v[206:209], v[72:75]
	s_setprio 0
	s_barrier
	s_add_i32 s0, s34, s52
	s_mov_b32 m0, s0
	ds_read_b128 v[210:213], v149
	ds_read_b128 v[214:217], v149 offset:1024
	ds_read_b128 v[218:221], v149 offset:2048
	global_load_lds_dwordx4 v130, s[42:43]
	s_add_i32 m0, s0, 0x2000
	ds_read_b128 v[222:225], v149 offset:3072
	global_load_lds_dwordx4 v134, s[42:43]
	s_barrier
	s_waitcnt lgkmcnt(0)
	s_setprio 1
	v_mfma_f32_16x16x32_bf16 v[116:119], v[210:213], v[170:173], 0
	v_mfma_f32_16x16x32_bf16 v[112:115], v[218:221], v[170:173], 0
	v_mfma_f32_16x16x32_bf16 v[100:103], v[210:213], v[178:181], 0
	v_mfma_f32_16x16x32_bf16 v[96:99], v[218:221], v[178:181], 0
	v_mfma_f32_16x16x32_bf16 v[84:87], v[210:213], v[194:197], 0
	v_mfma_f32_16x16x32_bf16 v[80:83], v[218:221], v[194:197], 0
	v_mfma_f32_16x16x32_bf16 v[68:71], v[210:213], v[202:205], 0
	v_mfma_f32_16x16x32_bf16 v[64:67], v[218:221], v[202:205], 0
	v_mfma_f32_16x16x32_bf16 v[116:119], v[214:217], v[174:177], v[116:119]
	v_mfma_f32_16x16x32_bf16 v[112:115], v[222:225], v[174:177], v[112:115]
	v_mfma_f32_16x16x32_bf16 v[100:103], v[214:217], v[188:191], v[100:103]
	v_mfma_f32_16x16x32_bf16 v[96:99], v[222:225], v[188:191], v[96:99]
	v_mfma_f32_16x16x32_bf16 v[84:87], v[214:217], v[198:201], v[84:87]
	v_mfma_f32_16x16x32_bf16 v[80:83], v[222:225], v[198:201], v[80:83]
	v_mfma_f32_16x16x32_bf16 v[68:71], v[214:217], v[206:209], v[68:71]
	v_mfma_f32_16x16x32_bf16 v[64:67], v[222:225], v[206:209], v[64:67]
	s_setprio 0
	s_mov_b32 m0, s39
	s_barrier
	ds_read_b128 v[170:173], v148 offset:16384
	ds_read_b128 v[174:177], v148 offset:17408
	ds_read_b128 v[178:181], v148 offset:18432
	ds_read_b128 v[188:191], v148 offset:19456
	ds_read_b128 v[194:197], v148 offset:20480
	ds_read_b128 v[198:201], v148 offset:21504
	ds_read_b128 v[202:205], v148 offset:22528
	global_load_lds_dwordx4 v128, s[44:45]
	s_mov_b32 m0, s53
	ds_read_b128 v[206:209], v148 offset:23552
	global_load_lds_dwordx4 v132, s[44:45]
	s_barrier
	s_waitcnt lgkmcnt(0)
	s_setprio 1
	v_mfma_f32_16x16x32_bf16 v[60:63], v[150:153], v[170:173], 0
	v_mfma_f32_16x16x32_bf16 v[56:59], v[162:165], v[170:173], 0
	v_mfma_f32_16x16x32_bf16 v[44:47], v[150:153], v[178:181], 0
	v_mfma_f32_16x16x32_bf16 v[40:43], v[162:165], v[178:181], 0
	v_mfma_f32_16x16x32_bf16 v[28:31], v[150:153], v[194:197], 0
	v_mfma_f32_16x16x32_bf16 v[24:27], v[162:165], v[194:197], 0
	v_mfma_f32_16x16x32_bf16 v[12:15], v[150:153], v[202:205], 0
	v_mfma_f32_16x16x32_bf16 v[8:11], v[162:165], v[202:205], 0
	v_mfma_f32_16x16x32_bf16 v[60:63], v[154:157], v[174:177], v[60:63]
	v_mfma_f32_16x16x32_bf16 v[56:59], v[166:169], v[174:177], v[56:59]
	v_mfma_f32_16x16x32_bf16 v[44:47], v[154:157], v[188:191], v[44:47]
	v_mfma_f32_16x16x32_bf16 v[40:43], v[166:169], v[188:191], v[40:43]
	v_mfma_f32_16x16x32_bf16 v[28:31], v[154:157], v[198:201], v[28:31]
	v_mfma_f32_16x16x32_bf16 v[24:27], v[166:169], v[198:201], v[24:27]
	v_mfma_f32_16x16x32_bf16 v[12:15], v[154:157], v[206:209], v[12:15]
	v_mfma_f32_16x16x32_bf16 v[8:11], v[166:169], v[206:209], v[8:11]
	s_setprio 0
	s_barrier
; #define PG8_STAGE(bufoff, gbase, voff) do { _Pragma("unroll") for (int _i = 0; _i < 2; ++_i) \
;         __builtin_amdgcn_global_load_lds((const unsigned*)((const char*)(gbase) + (voff)[_i]), (LAS unsigned*)(lds + (bufoff) + ldsw + _i * 8192), 16, 0, 0); } while (0)
; #define PG8_LDA(dst, b, h) do { _Pragma("unroll") for (int m = 0; m < 4; ++m) _Pragma("unroll") for (int k = 0; k < 2; ++k) dst[m][k] = *(const LAS bf16x8*)(lds + PG8_SA(b, h) + aoff + m * 2048 + k * 1024); } while (0)
; #define PG8_LDB(dst, b, h) do { _Pragma("unroll") for (int n = 0; n < 2; ++n) _Pragma("unroll") for (int k = 0; k < 2; ++k) dst[n][k] = *(const LAS bf16x8*)(lds + PG8_SB(b, h) + boff + n * 2048 + k * 1024); } while (0)
; #define PG8_MMA(ai, bj, At, Bt) do { __builtin_amdgcn_s_setprio(1); _Pragma("unroll") for (int m = 0; m < 4; ++m) _Pragma("unroll") for (int n = 0; n < 2; ++n) _Pragma("unroll") for (int k = 0; k < 2; ++k) \
;         acc[ai][bj][m][n] = __builtin_amdgcn_mfma_f32_16x16x32_bf16(Bt[n][k], At[m][k], acc[ai][bj][m][n], 0, 0, 0); __builtin_amdgcn_s_setprio(0); } while (0)
; #define PG8_WAIT_V(n) asm volatile("s_waitcnt vmcnt(" #n ")" ::: "memory")
; #define PG8_WAIT_L(n) asm volatile("s_waitcnt lgkmcnt(" #n ")" ::: "memory")
; #define PG8_BAR __builtin_amdgcn_s_barrier()
; #define PG8_SCHED __builtin_amdgcn_sched_barrier(0)
; template <class Epi, class Sched>
; DI void gemm_phase(LAS unsigned char* lds, const Gemm g, const Sched& S, const Epi& E) {
;     ...
;             PG8_STAGE(PG8_SB(0, 1), b2 + hstep, voffB);
;             PG8_WAIT_V(6); PG8_BAR; PG8_MMA(1, 1, At, B1); PG8_BAR;
;             PG8_LDB(B0, 1, 0); PG8_SCHED; PG8_LDA(At, 1, 0); PG8_STAGE(PG8_SA(0, 1), a2 + hstep, voffA);
;             PG8_WAIT_L(8); PG8_BAR; PG8_WAIT_L(0); PG8_MMA(0, 0, At, B0); PG8_BAR; PG8_SCHED;
;             PG8_LDB(B1, 1, 1); PG8_STAGE(PG8_SB(1, 0), b3, voffB);
;             PG8_BAR; PG8_WAIT_L(0); PG8_MMA(0, 1, At, B1); PG8_BAR;
;             PG8_LDA(At, 1, 1); PG8_STAGE(PG8_SA(1, 0), a3, voffA);
	s_add_u32 s0, s42, 0x80000
	s_addc_u32 s1, s43, 0
	s_add_i32 s4, s35, s52
	s_mov_b32 m0, s4
	s_nop 0
	global_load_lds_dwordx4 v130, s[0:1]
	s_add_i32 m0, s4, 0x2000
	s_nop 0
	global_load_lds_dwordx4 v134, s[0:1]
	s_waitcnt vmcnt(6)
	s_barrier
	s_setprio 1
	v_mfma_f32_16x16x32_bf16 v[52:55], v[210:213], v[170:173], 0
	v_mfma_f32_16x16x32_bf16 v[48:51], v[218:221], v[170:173], 0
	v_mfma_f32_16x16x32_bf16 v[36:39], v[210:213], v[178:181], 0
	v_mfma_f32_16x16x32_bf16 v[32:35], v[218:221], v[178:181], 0
	v_mfma_f32_16x16x32_bf16 v[20:23], v[210:213], v[194:197], 0
	v_mfma_f32_16x16x32_bf16 v[16:19], v[218:221], v[194:197], 0
	v_mfma_f32_16x16x32_bf16 v[4:7], v[210:213], v[202:205], 0
	v_mfma_f32_16x16x32_bf16 v[0:3], v[218:221], v[202:205], 0
	v_mfma_f32_16x16x32_bf16 v[52:55], v[214:217], v[174:177], v[52:55]
	v_mfma_f32_16x16x32_bf16 v[48:51], v[222:225], v[174:177], v[48:51]
	v_mfma_f32_16x16x32_bf16 v[36:39], v[214:217], v[188:191], v[36:39]
	v_mfma_f32_16x16x32_bf16 v[32:35], v[222:225], v[188:191], v[32:35]
	v_mfma_f32_16x16x32_bf16 v[20:23], v[214:217], v[198:201], v[20:23]
	v_mfma_f32_16x16x32_bf16 v[16:19], v[222:225], v[198:201], v[16:19]
	v_mfma_f32_16x16x32_bf16 v[4:7], v[214:217], v[206:209], v[4:7]
	v_mfma_f32_16x16x32_bf16 v[0:3], v[222:225], v[206:209], v[0:3]
	s_setprio 0
	s_add_i32 s4, 0, 0x18000
	v_add_u32_e32 v161, s4, v146
	s_barrier
	ds_read_b128 v[150:153], v161
	ds_read_b128 v[154:157], v161 offset:1024
	ds_read_b128 v[162:165], v161 offset:2048
	ds_read_b128 v[166:169], v161 offset:3072
	s_add_u32 s0, s44, 0x80000
	s_addc_u32 s1, s45, 0
	s_mov_b32 m0, s54
	ds_read_b128 v[170:173], v148 offset:32768
	ds_read_b128 v[174:177], v148 offset:33792
	ds_read_b128 v[178:181], v148 offset:34816
	ds_read_b128 v[188:191], v148 offset:35840
	ds_read_b128 v[194:197], v148 offset:36864
	ds_read_b128 v[198:201], v148 offset:37888
	ds_read_b128 v[202:205], v148 offset:38912
	global_load_lds_dwordx4 v128, s[0:1]
	s_mov_b32 m0, s55
	ds_read_b128 v[206:209], v148 offset:39936
	global_load_lds_dwordx4 v132, s[0:1]
	s_waitcnt lgkmcnt(8)
	s_barrier
	s_waitcnt lgkmcnt(0)
	s_setprio 1
	v_mfma_f32_16x16x32_bf16 v[124:127], v[150:153], v[170:173], v[124:127]
	v_mfma_f32_16x16x32_bf16 v[120:123], v[162:165], v[170:173], v[120:123]
	v_mfma_f32_16x16x32_bf16 v[108:111], v[150:153], v[178:181], v[108:111]
	v_mfma_f32_16x16x32_bf16 v[104:107], v[162:165], v[178:181], v[104:107]
	v_mfma_f32_16x16x32_bf16 v[92:95], v[150:153], v[194:197], v[92:95]
	v_mfma_f32_16x16x32_bf16 v[88:91], v[162:165], v[194:197], v[88:91]
	v_mfma_f32_16x16x32_bf16 v[76:79], v[150:153], v[202:205], v[76:79]
	v_mfma_f32_16x16x32_bf16 v[72:75], v[162:165], v[202:205], v[72:75]
	v_mfma_f32_16x16x32_bf16 v[124:127], v[154:157], v[174:177], v[124:127]
	v_mfma_f32_16x16x32_bf16 v[120:123], v[166:169], v[174:177], v[120:123]
	v_mfma_f32_16x16x32_bf16 v[108:111], v[154:157], v[188:191], v[108:111]
	v_mfma_f32_16x16x32_bf16 v[104:107], v[166:169], v[188:191], v[104:107]
	v_mfma_f32_16x16x32_bf16 v[92:95], v[154:157], v[198:201], v[92:95]
	v_mfma_f32_16x16x32_bf16 v[88:91], v[166:169], v[198:201], v[88:91]
	v_mfma_f32_16x16x32_bf16 v[76:79], v[154:157], v[206:209], v[76:79]
	v_mfma_f32_16x16x32_bf16 v[72:75], v[166:169], v[206:209], v[72:75]
	s_setprio 0
	s_barrier
	s_add_i32 s5, 0, 0x1c000
	s_add_i32 s0, s4, s52
	v_add_u32_e32 v161, s5, v146
	s_add_i32 m0, s0, 0xffffff80
	ds_read_b128 v[210:213], v161
	ds_read_b128 v[214:217], v161 offset:1024
	ds_read_b128 v[218:221], v161 offset:2048
	global_load_lds_dwordx4 v130, s[42:43] offset:128
	s_add_i32 m0, s0, 0x1f80
	ds_read_b128 v[222:225], v161 offset:3072
	global_load_lds_dwordx4 v134, s[42:43] offset:128
	s_barrier
	s_waitcnt lgkmcnt(0)
	s_setprio 1
	v_mfma_f32_16x16x32_bf16 v[116:119], v[210:213], v[170:173], v[116:119]
	v_mfma_f32_16x16x32_bf16 v[112:115], v[218:221], v[170:173], v[112:115]
	v_mfma_f32_16x16x32_bf16 v[100:103], v[210:213], v[178:181], v[100:103]
	v_mfma_f32_16x16x32_bf16 v[96:99], v[218:221], v[178:181], v[96:99]
	v_mfma_f32_16x16x32_bf16 v[84:87], v[210:213], v[194:197], v[84:87]
	v_mfma_f32_16x16x32_bf16 v[80:83], v[218:221], v[194:197], v[80:83]
	v_mfma_f32_16x16x32_bf16 v[68:71], v[210:213], v[202:205], v[68:71]
	v_mfma_f32_16x16x32_bf16 v[64:67], v[218:221], v[202:205], v[64:67]
	v_mfma_f32_16x16x32_bf16 v[116:119], v[214:217], v[174:177], v[116:119]
	v_mfma_f32_16x16x32_bf16 v[112:115], v[222:225], v[174:177], v[112:115]
	v_mfma_f32_16x16x32_bf16 v[100:103], v[214:217], v[188:191], v[100:103]
	v_mfma_f32_16x16x32_bf16 v[96:99], v[222:225], v[188:191], v[96:99]
	v_mfma_f32_16x16x32_bf16 v[84:87], v[214:217], v[198:201], v[84:87]
	v_mfma_f32_16x16x32_bf16 v[80:83], v[222:225], v[198:201], v[80:83]
	v_mfma_f32_16x16x32_bf16 v[68:71], v[214:217], v[206:209], v[68:71]
	v_mfma_f32_16x16x32_bf16 v[64:67], v[222:225], v[206:209], v[64:67]
	s_setprio 0
	s_add_i32 m0, s59, 0xffffff80
	s_barrier
	ds_read_b128 v[170:173], v148 offset:49152
	ds_read_b128 v[174:177], v148 offset:50176
	ds_read_b128 v[178:181], v148 offset:51200
	ds_read_b128 v[188:191], v148 offset:52224
	ds_read_b128 v[194:197], v148 offset:53248
	ds_read_b128 v[198:201], v148 offset:54272
	ds_read_b128 v[202:205], v148 offset:55296
	global_load_lds_dwordx4 v128, s[44:45] offset:128
	s_add_i32 m0, s60, 0xffffff80
	ds_read_b128 v[206:209], v148 offset:56320
	global_load_lds_dwordx4 v132, s[44:45] offset:128
	s_barrier
; #define PG8_STAGE(bufoff, gbase, voff) do { _Pragma("unroll") for (int _i = 0; _i < 2; ++_i) \
;         __builtin_amdgcn_global_load_lds((const unsigned*)((const char*)(gbase) + (voff)[_i]), (LAS unsigned*)(lds + (bufoff) + ldsw + _i * 8192), 16, 0, 0); } while (0)
; #define PG8_LDA(dst, b, h) do { _Pragma("unroll") for (int m = 0; m < 4; ++m) _Pragma("unroll") for (int k = 0; k < 2; ++k) dst[m][k] = *(const LAS bf16x8*)(lds + PG8_SA(b, h) + aoff + m * 2048 + k * 1024); } while (0)
; #define PG8_LDB(dst, b, h) do { _Pragma("unroll") for (int n = 0; n < 2; ++n) _Pragma("unroll") for (int k = 0; k < 2; ++k) dst[n][k] = *(const LAS bf16x8*)(lds + PG8_SB(b, h) + boff + n * 2048 + k * 1024); } while (0)
; #define PG8_WAIT_V(n) asm volatile("s_waitcnt vmcnt(" #n ")" ::: "memory")
; #define PG8_WAIT_L(n) asm volatile("s_waitcnt lgkmcnt(" #n ")" ::: "memory")
; #define PG8_BAR __builtin_amdgcn_s_barrier()
; #define PG8_SCHED __builtin_amdgcn_sched_barrier(0)
; template <class Epi, class Sched>
; DI void gemm_phase(LAS unsigned char* lds, const Gemm g, const Sched& S, const Epi& E) {
;     ...
;             PG8_LDB(B0, 0, 0); PG8_SCHED; PG8_LDA(At, 0, 0); PG8_STAGE(PG8_SA(1, 1), a1 + hstep, voffA);
;             PG8_WAIT_L(8); PG8_BAR; PG8_WAIT_L(0); PG8_MMA(0, 0, At, B0); PG8_BAR; PG8_SCHED;
;             PG8_LDB(B1, 0, 1); PG8_STAGE(PG8_SB(0, 0), b2, voffB);
;             PG8_BAR; PG8_WAIT_L(0); PG8_MMA(0, 1, At, B1); PG8_BAR;
;             PG8_LDA(At, 0, 1); PG8_STAGE(PG8_SA(0, 0), a2, voffA);
;             PG8_BAR; PG8_WAIT_L(0); PG8_MMA(1, 0, At, B0); PG8_BAR; PG8_SCHED;
;             PG8_STAGE(PG8_SB(0, 1), b2 + hstep, voffB);
;             PG8_WAIT_V(6); PG8_BAR; PG8_MMA(1, 1, At, B1); PG8_BAR;
;             PG8_LDB(B0, 1, 0); PG8_SCHED; PG8_LDA(At, 1, 0); PG8_STAGE(PG8_SA(0, 1), a2 + hstep, voffA);
;             PG8_WAIT_L(8); PG8_BAR; PG8_WAIT_L(0); PG8_MMA(0, 0, At, B0); PG8_BAR; PG8_SCHED;
;             PG8_LDB(B1, 1, 1); PG8_STAGE(PG8_SB(1, 0), b3, voffB);
;             PG8_BAR; PG8_WAIT_L(0); PG8_MMA(0, 1, At, B1); PG8_BAR;
;             PG8_LDA(At, 1, 1); PG8_STAGE(PG8_SA(1, 0), a3, voffA);
;             PG8_BAR; PG8_WAIT_L(0); PG8_MMA(1, 0, At, B0); PG8_BAR; PG8_SCHED;
;             PG8_STAGE(PG8_SB(1, 1), b3 + hstep, voffB);
;             PG8_WAIT_V(6); PG8_BAR; PG8_MMA(1, 1, At, B1); PG8_BAR;
	s_waitcnt lgkmcnt(0)
	s_setprio 1
	v_mfma_f32_16x16x32_bf16 v[60:63], v[150:153], v[170:173], v[60:63]
	v_mfma_f32_16x16x32_bf16 v[56:59], v[162:165], v[170:173], v[56:59]
	v_mfma_f32_16x16x32_bf16 v[44:47], v[150:153], v[178:181], v[44:47]
	v_mfma_f32_16x16x32_bf16 v[40:43], v[162:165], v[178:181], v[40:43]
	v_mfma_f32_16x16x32_bf16 v[28:31], v[150:153], v[194:197], v[28:31]
	v_mfma_f32_16x16x32_bf16 v[24:27], v[162:165], v[194:197], v[24:27]
	v_mfma_f32_16x16x32_bf16 v[12:15], v[150:153], v[202:205], v[12:15]
	v_mfma_f32_16x16x32_bf16 v[8:11], v[162:165], v[202:205], v[8:11]
	v_mfma_f32_16x16x32_bf16 v[60:63], v[154:157], v[174:177], v[60:63]
	v_mfma_f32_16x16x32_bf16 v[56:59], v[166:169], v[174:177], v[56:59]
	v_mfma_f32_16x16x32_bf16 v[44:47], v[154:157], v[188:191], v[44:47]
	v_mfma_f32_16x16x32_bf16 v[40:43], v[166:169], v[188:191], v[40:43]
	v_mfma_f32_16x16x32_bf16 v[28:31], v[154:157], v[198:201], v[28:31]
	v_mfma_f32_16x16x32_bf16 v[24:27], v[166:169], v[198:201], v[24:27]
	v_mfma_f32_16x16x32_bf16 v[12:15], v[154:157], v[206:209], v[12:15]
	v_mfma_f32_16x16x32_bf16 v[8:11], v[166:169], v[206:209], v[8:11]
	s_setprio 0
	s_barrier
	s_add_u32 s0, s42, 0x80080
	s_addc_u32 s1, s43, 0
	s_add_i32 s4, s5, s52
	s_mov_b32 m0, s4
	s_nop 0
	global_load_lds_dwordx4 v130, s[0:1]
	s_add_i32 m0, s4, 0x2000
	s_nop 0
	global_load_lds_dwordx4 v134, s[0:1]
	s_waitcnt vmcnt(6)
	s_barrier
	s_setprio 1
	v_mfma_f32_16x16x32_bf16 v[52:55], v[210:213], v[170:173], v[52:55]
	v_mfma_f32_16x16x32_bf16 v[48:51], v[218:221], v[170:173], v[48:51]
	v_mfma_f32_16x16x32_bf16 v[36:39], v[210:213], v[178:181], v[36:39]
	v_mfma_f32_16x16x32_bf16 v[32:35], v[218:221], v[178:181], v[32:35]
	v_mfma_f32_16x16x32_bf16 v[20:23], v[210:213], v[194:197], v[20:23]
	v_mfma_f32_16x16x32_bf16 v[16:19], v[218:221], v[194:197], v[16:19]
	v_mfma_f32_16x16x32_bf16 v[4:7], v[210:213], v[202:205], v[4:7]
	v_mfma_f32_16x16x32_bf16 v[0:3], v[218:221], v[202:205], v[0:3]
	v_mfma_f32_16x16x32_bf16 v[52:55], v[214:217], v[174:177], v[52:55]
	v_mfma_f32_16x16x32_bf16 v[48:51], v[222:225], v[174:177], v[48:51]
	v_mfma_f32_16x16x32_bf16 v[36:39], v[214:217], v[188:191], v[36:39]
	v_mfma_f32_16x16x32_bf16 v[32:35], v[222:225], v[188:191], v[32:35]
	v_mfma_f32_16x16x32_bf16 v[20:23], v[214:217], v[198:201], v[20:23]
	v_mfma_f32_16x16x32_bf16 v[16:19], v[222:225], v[198:201], v[16:19]
	v_mfma_f32_16x16x32_bf16 v[4:7], v[214:217], v[206:209], v[4:7]
	v_mfma_f32_16x16x32_bf16 v[0:3], v[222:225], v[206:209], v[0:3]
	s_setprio 0
	s_add_i32 s69, s69, 2
	s_add_u32 s40, s40, 0x100
	s_addc_u32 s41, s41, 0
	s_add_u32 s67, s67, 0x100
	s_addc_u32 s68, s68, 0
	s_cmp_gt_u32 s69, 29
	s_barrier
	s_cbranch_scc0 .LBB0_219
	s_branch .Lpeel_done_219
.LBB0_219:
	ds_read_b128 v[150:153], v147
	ds_read_b128 v[154:157], v147 offset:1024
	ds_read_b128 v[162:165], v147 offset:2048
	ds_read_b128 v[166:169], v147 offset:3072
	s_add_u32 s0, s40, 0xfff80080
	s_addc_u32 s1, s41, -1
	s_cmp_eq_u32 s69, 28
	s_cselect_b32 s45, s17, s1
	s_cselect_b32 s44, s65, s0
	s_cselect_b32 s43, s15, s68
	s_cselect_b32 s42, s66, s67
	s_add_i32 m0, s39, 0xc000
	ds_read_b128 v[170:173], v148
	ds_read_b128 v[174:177], v148 offset:1024
	ds_read_b128 v[178:181], v148 offset:2048
	ds_read_b128 v[188:191], v148 offset:3072
	ds_read_b128 v[194:197], v148 offset:4096
	ds_read_b128 v[198:201], v148 offset:5120
	ds_read_b128 v[202:205], v148 offset:6144
	global_load_lds_dwordx4 v136, s[40:41]
	s_add_i32 m0, s39, 0xe000
	ds_read_b128 v[206:209], v148 offset:7168
	global_load_lds_dwordx4 v138, s[40:41]
	s_waitcnt lgkmcnt(8)
	s_barrier
	s_waitcnt lgkmcnt(0)
	s_setprio 1
	v_mfma_f32_16x16x32_bf16 v[124:127], v[150:153], v[170:173], v[124:127]
	v_mfma_f32_16x16x32_bf16 v[120:123], v[162:165], v[170:173], v[120:123]
	v_mfma_f32_16x16x32_bf16 v[108:111], v[150:153], v[178:181], v[108:111]
	v_mfma_f32_16x16x32_bf16 v[104:107], v[162:165], v[178:181], v[104:107]
	v_mfma_f32_16x16x32_bf16 v[92:95], v[150:153], v[194:197], v[92:95]
	v_mfma_f32_16x16x32_bf16 v[88:91], v[162:165], v[194:197], v[88:91]
	v_mfma_f32_16x16x32_bf16 v[76:79], v[150:153], v[202:205], v[76:79]
	v_mfma_f32_16x16x32_bf16 v[72:75], v[162:165], v[202:205], v[72:75]
	v_mfma_f32_16x16x32_bf16 v[124:127], v[154:157], v[174:177], v[124:127]
	v_mfma_f32_16x16x32_bf16 v[120:123], v[166:169], v[174:177], v[120:123]
	v_mfma_f32_16x16x32_bf16 v[108:111], v[154:157], v[188:191], v[108:111]
	v_mfma_f32_16x16x32_bf16 v[104:107], v[166:169], v[188:191], v[104:107]
	v_mfma_f32_16x16x32_bf16 v[92:95], v[154:157], v[198:201], v[92:95]
	v_mfma_f32_16x16x32_bf16 v[88:91], v[166:169], v[198:201], v[88:91]
	v_mfma_f32_16x16x32_bf16 v[76:79], v[154:157], v[206:209], v[76:79]
	v_mfma_f32_16x16x32_bf16 v[72:75], v[166:169], v[206:209], v[72:75]
	s_setprio 0
	s_barrier
	s_add_i32 s0, s34, s52
	s_mov_b32 m0, s0
	ds_read_b128 v[210:213], v149
	ds_read_b128 v[214:217], v149 offset:1024
	ds_read_b128 v[218:221], v149 offset:2048
	global_load_lds_dwordx4 v130, s[42:43]
	s_add_i32 m0, s0, 0x2000
	ds_read_b128 v[222:225], v149 offset:3072
	global_load_lds_dwordx4 v134, s[42:43]
	s_barrier
; #define PG8_STAGE(bufoff, gbase, voff) do { _Pragma("unroll") for (int _i = 0; _i < 2; ++_i) \
;         __builtin_amdgcn_global_load_lds((const unsigned*)((const char*)(gbase) + (voff)[_i]), (LAS unsigned*)(lds + (bufoff) + ldsw + _i * 8192), 16, 0, 0); } while (0)
; #define PG8_LDA(dst, b, h) do { _Pragma("unroll") for (int m = 0; m < 4; ++m) _Pragma("unroll") for (int k = 0; k < 2; ++k) dst[m][k] = *(const LAS bf16x8*)(lds + PG8_SA(b, h) + aoff + m * 2048 + k * 1024); } while (0)
; #define PG8_LDB(dst, b, h) do { _Pragma("unroll") for (int n = 0; n < 2; ++n) _Pragma("unroll") for (int k = 0; k < 2; ++k) dst[n][k] = *(const LAS bf16x8*)(lds + PG8_SB(b, h) + boff + n * 2048 + k * 1024); } while (0)
; #define PG8_MMA(ai, bj, At, Bt) do { __builtin_amdgcn_s_setprio(1); _Pragma("unroll") for (int m = 0; m < 4; ++m) _Pragma("unroll") for (int n = 0; n < 2; ++n) _Pragma("unroll") for (int k = 0; k < 2; ++k) \
;         acc[ai][bj][m][n] = __builtin_amdgcn_mfma_f32_16x16x32_bf16(Bt[n][k], At[m][k], acc[ai][bj][m][n], 0, 0, 0); __builtin_amdgcn_s_setprio(0); } while (0)
; #define PG8_WAIT_V(n) asm volatile("s_waitcnt vmcnt(" #n ")" ::: "memory")
; #define PG8_WAIT_L(n) asm volatile("s_waitcnt lgkmcnt(" #n ")" ::: "memory")
; #define PG8_BAR __builtin_amdgcn_s_barrier()
; #define PG8_SCHED __builtin_amdgcn_sched_barrier(0)
; template <class Epi, class Sched>
; DI void gemm_phase(LAS unsigned char* lds, const Gemm g, const Sched& S, const Epi& E) {
;     ...
;             PG8_BAR; PG8_WAIT_L(0); PG8_MMA(0, 1, At, B1); PG8_BAR;
;             PG8_LDA(At, 0, 1); PG8_STAGE(PG8_SA(0, 0), a2, voffA);
;             PG8_BAR; PG8_WAIT_L(0); PG8_MMA(1, 0, At, B0); PG8_BAR; PG8_SCHED;
;             PG8_STAGE(PG8_SB(0, 1), b2 + hstep, voffB);
;             PG8_WAIT_V(6); PG8_BAR; PG8_MMA(1, 1, At, B1); PG8_BAR;
;             PG8_LDB(B0, 1, 0); PG8_SCHED; PG8_LDA(At, 1, 0); PG8_STAGE(PG8_SA(0, 1), a2 + hstep, voffA);
;             PG8_WAIT_L(8); PG8_BAR; PG8_WAIT_L(0); PG8_MMA(0, 0, At, B0); PG8_BAR; PG8_SCHED;
	s_waitcnt lgkmcnt(0)
	s_setprio 1
	v_mfma_f32_16x16x32_bf16 v[116:119], v[210:213], v[170:173], v[116:119]
	v_mfma_f32_16x16x32_bf16 v[112:115], v[218:221], v[170:173], v[112:115]
	v_mfma_f32_16x16x32_bf16 v[100:103], v[210:213], v[178:181], v[100:103]
	v_mfma_f32_16x16x32_bf16 v[96:99], v[218:221], v[178:181], v[96:99]
	v_mfma_f32_16x16x32_bf16 v[84:87], v[210:213], v[194:197], v[84:87]
	v_mfma_f32_16x16x32_bf16 v[80:83], v[218:221], v[194:197], v[80:83]
	v_mfma_f32_16x16x32_bf16 v[68:71], v[210:213], v[202:205], v[68:71]
	v_mfma_f32_16x16x32_bf16 v[64:67], v[218:221], v[202:205], v[64:67]
	v_mfma_f32_16x16x32_bf16 v[116:119], v[214:217], v[174:177], v[116:119]
	v_mfma_f32_16x16x32_bf16 v[112:115], v[222:225], v[174:177], v[112:115]
	v_mfma_f32_16x16x32_bf16 v[100:103], v[214:217], v[188:191], v[100:103]
	v_mfma_f32_16x16x32_bf16 v[96:99], v[222:225], v[188:191], v[96:99]
	v_mfma_f32_16x16x32_bf16 v[84:87], v[214:217], v[198:201], v[84:87]
	v_mfma_f32_16x16x32_bf16 v[80:83], v[222:225], v[198:201], v[80:83]
	v_mfma_f32_16x16x32_bf16 v[68:71], v[214:217], v[206:209], v[68:71]
	v_mfma_f32_16x16x32_bf16 v[64:67], v[222:225], v[206:209], v[64:67]
	s_setprio 0
	s_mov_b32 m0, s39
	s_barrier
	ds_read_b128 v[170:173], v148 offset:16384
	ds_read_b128 v[174:177], v148 offset:17408
	ds_read_b128 v[178:181], v148 offset:18432
	ds_read_b128 v[188:191], v148 offset:19456
	ds_read_b128 v[194:197], v148 offset:20480
	ds_read_b128 v[198:201], v148 offset:21504
	ds_read_b128 v[202:205], v148 offset:22528
	global_load_lds_dwordx4 v128, s[44:45]
	s_mov_b32 m0, s53
	ds_read_b128 v[206:209], v148 offset:23552
	global_load_lds_dwordx4 v132, s[44:45]
	s_barrier
	s_waitcnt lgkmcnt(0)
	s_setprio 1
	v_mfma_f32_16x16x32_bf16 v[60:63], v[150:153], v[170:173], v[60:63]
	v_mfma_f32_16x16x32_bf16 v[56:59], v[162:165], v[170:173], v[56:59]
	v_mfma_f32_16x16x32_bf16 v[44:47], v[150:153], v[178:181], v[44:47]
	v_mfma_f32_16x16x32_bf16 v[40:43], v[162:165], v[178:181], v[40:43]
	v_mfma_f32_16x16x32_bf16 v[28:31], v[150:153], v[194:197], v[28:31]
	v_mfma_f32_16x16x32_bf16 v[24:27], v[162:165], v[194:197], v[24:27]
	v_mfma_f32_16x16x32_bf16 v[12:15], v[150:153], v[202:205], v[12:15]
	v_mfma_f32_16x16x32_bf16 v[8:11], v[162:165], v[202:205], v[8:11]
	v_mfma_f32_16x16x32_bf16 v[60:63], v[154:157], v[174:177], v[60:63]
	v_mfma_f32_16x16x32_bf16 v[56:59], v[166:169], v[174:177], v[56:59]
	v_mfma_f32_16x16x32_bf16 v[44:47], v[154:157], v[188:191], v[44:47]
	v_mfma_f32_16x16x32_bf16 v[40:43], v[166:169], v[188:191], v[40:43]
	v_mfma_f32_16x16x32_bf16 v[28:31], v[154:157], v[198:201], v[28:31]
	v_mfma_f32_16x16x32_bf16 v[24:27], v[166:169], v[198:201], v[24:27]
	v_mfma_f32_16x16x32_bf16 v[12:15], v[154:157], v[206:209], v[12:15]
	v_mfma_f32_16x16x32_bf16 v[8:11], v[166:169], v[206:209], v[8:11]
	s_setprio 0
	s_barrier
	s_add_u32 s0, s42, 0x80000
	s_addc_u32 s1, s43, 0
	s_add_i32 s4, s35, s52
	s_mov_b32 m0, s4
	s_nop 0
	global_load_lds_dwordx4 v130, s[0:1]
	s_add_i32 m0, s4, 0x2000
	s_nop 0
	global_load_lds_dwordx4 v134, s[0:1]
	s_waitcnt vmcnt(6)
	s_barrier
	s_setprio 1
	v_mfma_f32_16x16x32_bf16 v[52:55], v[210:213], v[170:173], v[52:55]
	v_mfma_f32_16x16x32_bf16 v[48:51], v[218:221], v[170:173], v[48:51]
	v_mfma_f32_16x16x32_bf16 v[36:39], v[210:213], v[178:181], v[36:39]
	v_mfma_f32_16x16x32_bf16 v[32:35], v[218:221], v[178:181], v[32:35]
	v_mfma_f32_16x16x32_bf16 v[20:23], v[210:213], v[194:197], v[20:23]
	v_mfma_f32_16x16x32_bf16 v[16:19], v[218:221], v[194:197], v[16:19]
	v_mfma_f32_16x16x32_bf16 v[4:7], v[210:213], v[202:205], v[4:7]
	v_mfma_f32_16x16x32_bf16 v[0:3], v[218:221], v[202:205], v[0:3]
	v_mfma_f32_16x16x32_bf16 v[52:55], v[214:217], v[174:177], v[52:55]
	v_mfma_f32_16x16x32_bf16 v[48:51], v[222:225], v[174:177], v[48:51]
	v_mfma_f32_16x16x32_bf16 v[36:39], v[214:217], v[188:191], v[36:39]
	v_mfma_f32_16x16x32_bf16 v[32:35], v[222:225], v[188:191], v[32:35]
	v_mfma_f32_16x16x32_bf16 v[20:23], v[214:217], v[198:201], v[20:23]
	v_mfma_f32_16x16x32_bf16 v[16:19], v[222:225], v[198:201], v[16:19]
	v_mfma_f32_16x16x32_bf16 v[4:7], v[214:217], v[206:209], v[4:7]
	v_mfma_f32_16x16x32_bf16 v[0:3], v[222:225], v[206:209], v[0:3]
	s_setprio 0
	s_add_i32 s4, 0, 0x18000
	v_add_u32_e32 v161, s4, v146
	s_barrier
	ds_read_b128 v[150:153], v161
	ds_read_b128 v[154:157], v161 offset:1024
	ds_read_b128 v[162:165], v161 offset:2048
	ds_read_b128 v[166:169], v161 offset:3072
	s_add_u32 s0, s44, 0x80000
	s_addc_u32 s1, s45, 0
	s_mov_b32 m0, s54
	ds_read_b128 v[170:173], v148 offset:32768
	ds_read_b128 v[174:177], v148 offset:33792
	ds_read_b128 v[178:181], v148 offset:34816
	ds_read_b128 v[188:191], v148 offset:35840
	ds_read_b128 v[194:197], v148 offset:36864
	ds_read_b128 v[198:201], v148 offset:37888
	ds_read_b128 v[202:205], v148 offset:38912
	global_load_lds_dwordx4 v128, s[0:1]
	s_mov_b32 m0, s55
	ds_read_b128 v[206:209], v148 offset:39936
	global_load_lds_dwordx4 v132, s[0:1]
	s_waitcnt lgkmcnt(8)
	s_barrier
; #define PG8_STAGE(bufoff, gbase, voff) do { _Pragma("unroll") for (int _i = 0; _i < 2; ++_i) \
;         __builtin_amdgcn_global_load_lds((const unsigned*)((const char*)(gbase) + (voff)[_i]), (LAS unsigned*)(lds + (bufoff) + ldsw + _i * 8192), 16, 0, 0); } while (0)
; #define PG8_LDA(dst, b, h) do { _Pragma("unroll") for (int m = 0; m < 4; ++m) _Pragma("unroll") for (int k = 0; k < 2; ++k) dst[m][k] = *(const LAS bf16x8*)(lds + PG8_SA(b, h) + aoff + m * 2048 + k * 1024); } while (0)
; #define PG8_LDB(dst, b, h) do { _Pragma("unroll") for (int n = 0; n < 2; ++n) _Pragma("unroll") for (int k = 0; k < 2; ++k) dst[n][k] = *(const LAS bf16x8*)(lds + PG8_SB(b, h) + boff + n * 2048 + k * 1024); } while (0)
; #define PG8_MMA(ai, bj, At, Bt) do { __builtin_amdgcn_s_setprio(1); _Pragma("unroll") for (int m = 0; m < 4; ++m) _Pragma("unroll") for (int n = 0; n < 2; ++n) _Pragma("unroll") for (int k = 0; k < 2; ++k) \
;         acc[ai][bj][m][n] = __builtin_amdgcn_mfma_f32_16x16x32_bf16(Bt[n][k], At[m][k], acc[ai][bj][m][n], 0, 0, 0); __builtin_amdgcn_s_setprio(0); } while (0)
; #define PG8_WAIT_V(n) asm volatile("s_waitcnt vmcnt(" #n ")" ::: "memory")
; #define PG8_WAIT_L(n) asm volatile("s_waitcnt lgkmcnt(" #n ")" ::: "memory")
; #define PG8_BAR __builtin_amdgcn_s_barrier()
; #define PG8_SCHED __builtin_amdgcn_sched_barrier(0)
; template <class Epi, class Sched>
; DI void gemm_phase(LAS unsigned char* lds, const Gemm g, const Sched& S, const Epi& E) {
;     ...
;             PG8_WAIT_L(8); PG8_BAR; PG8_WAIT_L(0); PG8_MMA(0, 0, At, B0); PG8_BAR; PG8_SCHED;
;             PG8_LDB(B1, 1, 1); PG8_STAGE(PG8_SB(1, 0), b3, voffB);
;             PG8_BAR; PG8_WAIT_L(0); PG8_MMA(0, 1, At, B1); PG8_BAR;
;             PG8_LDA(At, 1, 1); PG8_STAGE(PG8_SA(1, 0), a3, voffA);
;             PG8_BAR; PG8_WAIT_L(0); PG8_MMA(1, 0, At, B0); PG8_BAR; PG8_SCHED;
;             PG8_STAGE(PG8_SB(1, 1), b3 + hstep, voffB);
;             PG8_WAIT_V(6); PG8_BAR; PG8_MMA(1, 1, At, B1); PG8_BAR;
;         }
	s_waitcnt lgkmcnt(0)
	s_setprio 1
	v_mfma_f32_16x16x32_bf16 v[124:127], v[150:153], v[170:173], v[124:127]
	v_mfma_f32_16x16x32_bf16 v[120:123], v[162:165], v[170:173], v[120:123]
	v_mfma_f32_16x16x32_bf16 v[108:111], v[150:153], v[178:181], v[108:111]
	v_mfma_f32_16x16x32_bf16 v[104:107], v[162:165], v[178:181], v[104:107]
	v_mfma_f32_16x16x32_bf16 v[92:95], v[150:153], v[194:197], v[92:95]
	v_mfma_f32_16x16x32_bf16 v[88:91], v[162:165], v[194:197], v[88:91]
	v_mfma_f32_16x16x32_bf16 v[76:79], v[150:153], v[202:205], v[76:79]
	v_mfma_f32_16x16x32_bf16 v[72:75], v[162:165], v[202:205], v[72:75]
	v_mfma_f32_16x16x32_bf16 v[124:127], v[154:157], v[174:177], v[124:127]
	v_mfma_f32_16x16x32_bf16 v[120:123], v[166:169], v[174:177], v[120:123]
	v_mfma_f32_16x16x32_bf16 v[108:111], v[154:157], v[188:191], v[108:111]
	v_mfma_f32_16x16x32_bf16 v[104:107], v[166:169], v[188:191], v[104:107]
	v_mfma_f32_16x16x32_bf16 v[92:95], v[154:157], v[198:201], v[92:95]
	v_mfma_f32_16x16x32_bf16 v[88:91], v[166:169], v[198:201], v[88:91]
	v_mfma_f32_16x16x32_bf16 v[76:79], v[154:157], v[206:209], v[76:79]
	v_mfma_f32_16x16x32_bf16 v[72:75], v[166:169], v[206:209], v[72:75]
	s_setprio 0
	s_barrier
	s_add_i32 s5, 0, 0x1c000
	s_add_i32 s0, s4, s52
	v_add_u32_e32 v161, s5, v146
	s_add_i32 m0, s0, 0xffffff80
	ds_read_b128 v[210:213], v161
	ds_read_b128 v[214:217], v161 offset:1024
	ds_read_b128 v[218:221], v161 offset:2048
	global_load_lds_dwordx4 v130, s[42:43] offset:128
	s_add_i32 m0, s0, 0x1f80
	ds_read_b128 v[222:225], v161 offset:3072
	global_load_lds_dwordx4 v134, s[42:43] offset:128
	s_barrier
	s_waitcnt lgkmcnt(0)
	s_setprio 1
	v_mfma_f32_16x16x32_bf16 v[116:119], v[210:213], v[170:173], v[116:119]
	v_mfma_f32_16x16x32_bf16 v[112:115], v[218:221], v[170:173], v[112:115]
	v_mfma_f32_16x16x32_bf16 v[100:103], v[210:213], v[178:181], v[100:103]
	v_mfma_f32_16x16x32_bf16 v[96:99], v[218:221], v[178:181], v[96:99]
	v_mfma_f32_16x16x32_bf16 v[84:87], v[210:213], v[194:197], v[84:87]
	v_mfma_f32_16x16x32_bf16 v[80:83], v[218:221], v[194:197], v[80:83]
	v_mfma_f32_16x16x32_bf16 v[68:71], v[210:213], v[202:205], v[68:71]
	v_mfma_f32_16x16x32_bf16 v[64:67], v[218:221], v[202:205], v[64:67]
	v_mfma_f32_16x16x32_bf16 v[116:119], v[214:217], v[174:177], v[116:119]
	v_mfma_f32_16x16x32_bf16 v[112:115], v[222:225], v[174:177], v[112:115]
	v_mfma_f32_16x16x32_bf16 v[100:103], v[214:217], v[188:191], v[100:103]
	v_mfma_f32_16x16x32_bf16 v[96:99], v[222:225], v[188:191], v[96:99]
	v_mfma_f32_16x16x32_bf16 v[84:87], v[214:217], v[198:201], v[84:87]
	v_mfma_f32_16x16x32_bf16 v[80:83], v[222:225], v[198:201], v[80:83]
	v_mfma_f32_16x16x32_bf16 v[68:71], v[214:217], v[206:209], v[68:71]
	v_mfma_f32_16x16x32_bf16 v[64:67], v[222:225], v[206:209], v[64:67]
	s_setprio 0
	s_add_i32 m0, s59, 0xffffff80
	s_barrier
	ds_read_b128 v[170:173], v148 offset:49152
	ds_read_b128 v[174:177], v148 offset:50176
	ds_read_b128 v[178:181], v148 offset:51200
	ds_read_b128 v[188:191], v148 offset:52224
	ds_read_b128 v[194:197], v148 offset:53248
	ds_read_b128 v[198:201], v148 offset:54272
	ds_read_b128 v[202:205], v148 offset:55296
	global_load_lds_dwordx4 v128, s[44:45] offset:128
	s_add_i32 m0, s60, 0xffffff80
	ds_read_b128 v[206:209], v148 offset:56320
	global_load_lds_dwordx4 v132, s[44:45] offset:128
	s_barrier
	s_waitcnt lgkmcnt(0)
	s_setprio 1
	v_mfma_f32_16x16x32_bf16 v[60:63], v[150:153], v[170:173], v[60:63]
	v_mfma_f32_16x16x32_bf16 v[56:59], v[162:165], v[170:173], v[56:59]
	v_mfma_f32_16x16x32_bf16 v[44:47], v[150:153], v[178:181], v[44:47]
	v_mfma_f32_16x16x32_bf16 v[40:43], v[162:165], v[178:181], v[40:43]
	v_mfma_f32_16x16x32_bf16 v[28:31], v[150:153], v[194:197], v[28:31]
	v_mfma_f32_16x16x32_bf16 v[24:27], v[162:165], v[194:197], v[24:27]
	v_mfma_f32_16x16x32_bf16 v[12:15], v[150:153], v[202:205], v[12:15]
	v_mfma_f32_16x16x32_bf16 v[8:11], v[162:165], v[202:205], v[8:11]
	v_mfma_f32_16x16x32_bf16 v[60:63], v[154:157], v[174:177], v[60:63]
	v_mfma_f32_16x16x32_bf16 v[56:59], v[166:169], v[174:177], v[56:59]
	v_mfma_f32_16x16x32_bf16 v[44:47], v[154:157], v[188:191], v[44:47]
	v_mfma_f32_16x16x32_bf16 v[40:43], v[166:169], v[188:191], v[40:43]
	v_mfma_f32_16x16x32_bf16 v[28:31], v[154:157], v[198:201], v[28:31]
	v_mfma_f32_16x16x32_bf16 v[24:27], v[166:169], v[198:201], v[24:27]
	v_mfma_f32_16x16x32_bf16 v[12:15], v[154:157], v[206:209], v[12:15]
	v_mfma_f32_16x16x32_bf16 v[8:11], v[166:169], v[206:209], v[8:11]
	s_setprio 0
	s_barrier
	s_add_u32 s0, s42, 0x80080
	s_addc_u32 s1, s43, 0
	s_add_i32 s4, s5, s52
	s_mov_b32 m0, s4
	s_nop 0
	global_load_lds_dwordx4 v130, s[0:1]
	s_add_i32 m0, s4, 0x2000
	s_nop 0
	global_load_lds_dwordx4 v134, s[0:1]
	s_waitcnt vmcnt(6)
	s_barrier
	s_setprio 1
	v_mfma_f32_16x16x32_bf16 v[52:55], v[210:213], v[170:173], v[52:55]
	v_mfma_f32_16x16x32_bf16 v[48:51], v[218:221], v[170:173], v[48:51]
	v_mfma_f32_16x16x32_bf16 v[36:39], v[210:213], v[178:181], v[36:39]
	v_mfma_f32_16x16x32_bf16 v[32:35], v[218:221], v[178:181], v[32:35]
	v_mfma_f32_16x16x32_bf16 v[20:23], v[210:213], v[194:197], v[20:23]
	v_mfma_f32_16x16x32_bf16 v[16:19], v[218:221], v[194:197], v[16:19]
	v_mfma_f32_16x16x32_bf16 v[4:7], v[210:213], v[202:205], v[4:7]
	v_mfma_f32_16x16x32_bf16 v[0:3], v[218:221], v[202:205], v[0:3]
	v_mfma_f32_16x16x32_bf16 v[52:55], v[214:217], v[174:177], v[52:55]
	v_mfma_f32_16x16x32_bf16 v[48:51], v[222:225], v[174:177], v[48:51]
	v_mfma_f32_16x16x32_bf16 v[36:39], v[214:217], v[188:191], v[36:39]
	v_mfma_f32_16x16x32_bf16 v[32:35], v[222:225], v[188:191], v[32:35]
	v_mfma_f32_16x16x32_bf16 v[20:23], v[214:217], v[198:201], v[20:23]
	v_mfma_f32_16x16x32_bf16 v[16:19], v[222:225], v[198:201], v[16:19]
	v_mfma_f32_16x16x32_bf16 v[4:7], v[214:217], v[206:209], v[4:7]
	v_mfma_f32_16x16x32_bf16 v[0:3], v[222:225], v[206:209], v[0:3]
	s_setprio 0
	s_add_i32 s69, s69, 2
	s_add_u32 s40, s40, 0x100
	s_addc_u32 s41, s41, 0
	s_add_u32 s67, s67, 0x100
	s_addc_u32 s68, s68, 0
	s_cmp_gt_u32 s69, 29
	s_barrier
	s_cbranch_scc0 .LBB0_219

;     DI size_t aoff(const Unit& u, size_t tstep) const { return (size_t)u.pm * tstep; }
;     DI size_t boff(const Unit& u, size_t tstep) const { return (size_t)u.pn * tstep; }
;     DI bool next(int i, Unit& u) const { const long L = (long)i * G + c; if (L >= np) return false; u.pm = pmv; u.pn = (int)(L % nN); u.ks = (int)(L / nN); return true; }
;     DI size_t aoff(const Unit& u, size_t) const { return (size_t)u.ks * kbytes; }
;     DI size_t boff(const Unit& u, size_t tstep) const { return (size_t)u.pn * tstep + (size_t)u.ks * kbytes; }
;     DI bool next(int i, Unit& u) const { Unit t; if (!S.next(i / 3, t)) return false; u.pm = t.pm; u.pn = t.pn; u.ks = i % 3; return true; }
;     DI size_t aoff(const Unit& u, size_t tstep) const { return (u.ks < 2 ? offU : offOA) + (size_t)u.pm * tstep; }
; #define PG8_WAIT_V(n) asm volatile("s_waitcnt vmcnt(" #n ")" ::: "memory")
; template <class Epi, class Sched>
; DI void gemm_phase(LAS unsigned char* lds, const Gemm g, const Sched& S, const Epi& E) {
;     ...
;         const bool has_next = S.next(ui + 1, nxt);
;         const char* nA = has_next ? (const char*)g.A + S.aoff(nxt, tstep) : cA; const char* nB = has_next ? (const char*)g.Bt + S.boff(nxt, tstep) : cB;
;         for (int t = 0; t < nt; t += 2) {
;             if constexpr (Epi::HAS_MID) { if (t == E.mid_t(nt)) { int fr3 = fr, fq3 = fq; asm volatile("" : "+v"(fr3), "+v"(fq3)); E.mid(acc, cur, wr, wc, fr3, fq3); } }
;             const bool last = (t == nt - 2);
;             const char* a1 = cA + (size_t)(t + 1) * kstep;
;             const char* a2 = last ? nA : cA + (size_t)(t + 2) * kstep; const char* b2 = last ? nB : cB + (size_t)(t + 2) * kstep;
;             const char* a3 = a2 + kstep; const char* b3 = b2 + kstep;
;             PG8_LDB(B0, 0, 0); PG8_SCHED; PG8_LDA(At, 0, 0); PG8_STAGE(PG8_SA(1, 1), a1 + hstep, voffA);
;             PG8_WAIT_L(8); PG8_BAR; PG8_WAIT_L(0); PG8_MMA(0, 0, At, B0); PG8_BAR; PG8_SCHED;
;             PG8_LDB(B1, 0, 1); PG8_STAGE(PG8_SB(0, 0), b2, voffB);
;             PG8_BAR; PG8_WAIT_L(0); PG8_MMA(0, 1, At, B1); PG8_BAR;
;             PG8_LDA(At, 0, 1); PG8_STAGE(PG8_SA(0, 0), a2, voffA);
;             PG8_BAR; PG8_WAIT_L(0); PG8_MMA(1, 0, At, B0); PG8_BAR; PG8_SCHED;
;             PG8_STAGE(PG8_SB(0, 1), b2 + hstep, voffB);
;             PG8_WAIT_V(6); PG8_BAR; PG8_MMA(1, 1, At, B1); PG8_BAR;
.LBB0_325:
	s_add_u32 s28, s40, s28
	s_addc_u32 s29, s41, s29
	s_and_b64 s[0:1], s[8:9], exec
	s_cselect_b32 s15, s29, s39
	s_cselect_b32 s17, s28, s38
	s_add_u32 s8, s38, 0x160080
	s_addc_u32 s9, s39, 0
	s_add_u32 s66, s36, 0x100
	v_mov_b32_e32 v0, 0
	s_addc_u32 s67, s37, 0
	s_mov_b32 s68, -2
	ds_read_b128 v[150:153], v141
	ds_read_b128 v[154:157], v141 offset:1024
	ds_read_b128 v[162:165], v141 offset:2048
	ds_read_b128 v[166:169], v141 offset:3072
	s_add_u32 s0, s8, 0xffea0080
	s_addc_u32 s1, s9, -1
	s_cmp_eq_u32 s68, 4
	s_cselect_b32 s39, s15, s1
	s_cselect_b32 s38, s17, s0
	s_cselect_b32 s37, s19, s67
	s_cselect_b32 s36, s18, s66
	s_mov_b32 m0, s58
	ds_read_b128 v[170:173], v142
	ds_read_b128 v[174:177], v142 offset:1024
	ds_read_b128 v[178:181], v142 offset:2048
	ds_read_b128 v[188:191], v142 offset:3072
	ds_read_b128 v[194:197], v142 offset:4096
	ds_read_b128 v[198:201], v142 offset:5120
	ds_read_b128 v[202:205], v142 offset:6144
	global_load_lds_dwordx4 v132, s[8:9]
	s_mov_b32 m0, s59
	ds_read_b128 v[206:209], v142 offset:7168
	global_load_lds_dwordx4 v134, s[8:9]
	s_waitcnt lgkmcnt(8)
	s_barrier
	s_waitcnt lgkmcnt(0)
	s_setprio 1
	v_mfma_f32_16x16x32_bf16 v[124:127], v[150:153], v[170:173], 0
	v_mfma_f32_16x16x32_bf16 v[120:123], v[162:165], v[170:173], 0
	v_mfma_f32_16x16x32_bf16 v[116:119], v[150:153], v[178:181], 0
	v_mfma_f32_16x16x32_bf16 v[112:115], v[162:165], v[178:181], 0
	v_mfma_f32_16x16x32_bf16 v[104:107], v[150:153], v[194:197], 0
	v_mfma_f32_16x16x32_bf16 v[96:99], v[162:165], v[194:197], 0
	v_mfma_f32_16x16x32_bf16 v[88:91], v[150:153], v[202:205], 0
	v_mfma_f32_16x16x32_bf16 v[80:83], v[162:165], v[202:205], 0
	v_mfma_f32_16x16x32_bf16 v[124:127], v[154:157], v[174:177], v[124:127]
	v_mfma_f32_16x16x32_bf16 v[120:123], v[166:169], v[174:177], v[120:123]
	v_mfma_f32_16x16x32_bf16 v[116:119], v[154:157], v[188:191], v[116:119]
	v_mfma_f32_16x16x32_bf16 v[112:115], v[166:169], v[188:191], v[112:115]
	v_mfma_f32_16x16x32_bf16 v[104:107], v[154:157], v[198:201], v[104:107]
	v_mfma_f32_16x16x32_bf16 v[96:99], v[166:169], v[198:201], v[96:99]
	v_mfma_f32_16x16x32_bf16 v[88:91], v[154:157], v[206:209], v[88:91]
	v_mfma_f32_16x16x32_bf16 v[80:83], v[166:169], v[206:209], v[80:83]
	s_setprio 0
	s_barrier
	s_mov_b32 m0, s60
	ds_read_b128 v[210:213], v143
	ds_read_b128 v[214:217], v143 offset:1024
	ds_read_b128 v[218:221], v143 offset:2048
	global_load_lds_dwordx4 v130, s[36:37]
	s_mov_b32 m0, s61
	ds_read_b128 v[222:225], v143 offset:3072
	global_load_lds_dwordx4 v128, s[36:37]
	s_barrier
	s_waitcnt lgkmcnt(0)
	s_setprio 1
	v_mfma_f32_16x16x32_bf16 v[108:111], v[210:213], v[170:173], 0
	v_mfma_f32_16x16x32_bf16 v[100:103], v[218:221], v[170:173], 0
	v_mfma_f32_16x16x32_bf16 v[92:95], v[210:213], v[178:181], 0
	v_mfma_f32_16x16x32_bf16 v[84:87], v[218:221], v[178:181], 0
	v_mfma_f32_16x16x32_bf16 v[76:79], v[210:213], v[194:197], 0
	v_mfma_f32_16x16x32_bf16 v[72:75], v[218:221], v[194:197], 0
	v_mfma_f32_16x16x32_bf16 v[68:71], v[210:213], v[202:205], 0
	v_mfma_f32_16x16x32_bf16 v[64:67], v[218:221], v[202:205], 0
	v_mfma_f32_16x16x32_bf16 v[108:111], v[214:217], v[174:177], v[108:111]
	v_mfma_f32_16x16x32_bf16 v[100:103], v[222:225], v[174:177], v[100:103]
	v_mfma_f32_16x16x32_bf16 v[92:95], v[214:217], v[188:191], v[92:95]
	v_mfma_f32_16x16x32_bf16 v[84:87], v[222:225], v[188:191], v[84:87]
	v_mfma_f32_16x16x32_bf16 v[76:79], v[214:217], v[198:201], v[76:79]
	v_mfma_f32_16x16x32_bf16 v[72:75], v[222:225], v[198:201], v[72:75]
	v_mfma_f32_16x16x32_bf16 v[68:71], v[214:217], v[206:209], v[68:71]
	v_mfma_f32_16x16x32_bf16 v[64:67], v[222:225], v[206:209], v[64:67]
	s_setprio 0
	s_mov_b32 m0, s42
	s_barrier
	ds_read_b128 v[170:173], v142 offset:16384
	ds_read_b128 v[174:177], v142 offset:17408
	ds_read_b128 v[178:181], v142 offset:18432
	ds_read_b128 v[188:191], v142 offset:19456
	ds_read_b128 v[194:197], v142 offset:20480
	ds_read_b128 v[198:201], v142 offset:21504
	ds_read_b128 v[202:205], v142 offset:22528
	global_load_lds_dwordx4 v130, s[38:39]
	s_mov_b32 m0, s43
	ds_read_b128 v[206:209], v142 offset:23552
	global_load_lds_dwordx4 v128, s[38:39]
	s_barrier
	s_waitcnt lgkmcnt(0)
	s_setprio 1
	v_mfma_f32_16x16x32_bf16 v[60:63], v[150:153], v[170:173], 0
	v_mfma_f32_16x16x32_bf16 v[56:59], v[162:165], v[170:173], 0
	v_mfma_f32_16x16x32_bf16 v[52:55], v[150:153], v[178:181], 0
	v_mfma_f32_16x16x32_bf16 v[48:51], v[162:165], v[178:181], 0
	v_mfma_f32_16x16x32_bf16 v[40:43], v[150:153], v[194:197], 0
	v_mfma_f32_16x16x32_bf16 v[32:35], v[162:165], v[194:197], 0
	v_mfma_f32_16x16x32_bf16 v[24:27], v[150:153], v[202:205], 0
	v_mfma_f32_16x16x32_bf16 v[16:19], v[162:165], v[202:205], 0
	v_mfma_f32_16x16x32_bf16 v[60:63], v[154:157], v[174:177], v[60:63]
	v_mfma_f32_16x16x32_bf16 v[56:59], v[166:169], v[174:177], v[56:59]
	v_mfma_f32_16x16x32_bf16 v[52:55], v[154:157], v[188:191], v[52:55]
	v_mfma_f32_16x16x32_bf16 v[48:51], v[166:169], v[188:191], v[48:51]
	v_mfma_f32_16x16x32_bf16 v[40:43], v[154:157], v[198:201], v[40:43]
	v_mfma_f32_16x16x32_bf16 v[32:35], v[166:169], v[198:201], v[32:35]
	v_mfma_f32_16x16x32_bf16 v[24:27], v[154:157], v[206:209], v[24:27]
	v_mfma_f32_16x16x32_bf16 v[16:19], v[166:169], v[206:209], v[16:19]
	s_setprio 0
	s_barrier
	s_add_u32 s0, s36, 0x160000
	s_addc_u32 s1, s37, 0
	s_mov_b32 m0, s62
	s_nop 0
	global_load_lds_dwordx4 v130, s[0:1]
	s_mov_b32 m0, s63
	s_nop 0
	global_load_lds_dwordx4 v128, s[0:1]
	s_waitcnt vmcnt(6)
	s_barrier
; #define PG8_STAGE(bufoff, gbase, voff) do { _Pragma("unroll") for (int _i = 0; _i < 2; ++_i) \
;         __builtin_amdgcn_global_load_lds((const unsigned*)((const char*)(gbase) + (voff)[_i]), (LAS unsigned*)(lds + (bufoff) + ldsw + _i * 8192), 16, 0, 0); } while (0)
; #define PG8_LDA(dst, b, h) do { _Pragma("unroll") for (int m = 0; m < 4; ++m) _Pragma("unroll") for (int k = 0; k < 2; ++k) dst[m][k] = *(const LAS bf16x8*)(lds + PG8_SA(b, h) + aoff + m * 2048 + k * 1024); } while (0)
; #define PG8_LDB(dst, b, h) do { _Pragma("unroll") for (int n = 0; n < 2; ++n) _Pragma("unroll") for (int k = 0; k < 2; ++k) dst[n][k] = *(const LAS bf16x8*)(lds + PG8_SB(b, h) + boff + n * 2048 + k * 1024); } while (0)
; #define PG8_MMA(ai, bj, At, Bt) do { __builtin_amdgcn_s_setprio(1); _Pragma("unroll") for (int m = 0; m < 4; ++m) _Pragma("unroll") for (int n = 0; n < 2; ++n) _Pragma("unroll") for (int k = 0; k < 2; ++k) \
;         acc[ai][bj][m][n] = __builtin_amdgcn_mfma_f32_16x16x32_bf16(Bt[n][k], At[m][k], acc[ai][bj][m][n], 0, 0, 0); __builtin_amdgcn_s_setprio(0); } while (0)
; #define PG8_WAIT_V(n) asm volatile("s_waitcnt vmcnt(" #n ")" ::: "memory")
; #define PG8_WAIT_L(n) asm volatile("s_waitcnt lgkmcnt(" #n ")" ::: "memory")
; #define PG8_BAR __builtin_amdgcn_s_barrier()
; #define PG8_SCHED __builtin_amdgcn_sched_barrier(0)
; template <class Epi, class Sched>
; DI void gemm_phase(LAS unsigned char* lds, const Gemm g, const Sched& S, const Epi& E) {
;     ...
;             PG8_WAIT_V(6); PG8_BAR; PG8_MMA(1, 1, At, B1); PG8_BAR;
;             PG8_LDB(B0, 1, 0); PG8_SCHED; PG8_LDA(At, 1, 0); PG8_STAGE(PG8_SA(0, 1), a2 + hstep, voffA);
;             PG8_WAIT_L(8); PG8_BAR; PG8_WAIT_L(0); PG8_MMA(0, 0, At, B0); PG8_BAR; PG8_SCHED;
;             PG8_LDB(B1, 1, 1); PG8_STAGE(PG8_SB(1, 0), b3, voffB);
;             PG8_BAR; PG8_WAIT_L(0); PG8_MMA(0, 1, At, B1); PG8_BAR;
;             PG8_LDA(At, 1, 1); PG8_STAGE(PG8_SA(1, 0), a3, voffA);
	s_setprio 1
	v_mfma_f32_16x16x32_bf16 v[44:47], v[210:213], v[170:173], 0
	v_mfma_f32_16x16x32_bf16 v[36:39], v[218:221], v[170:173], 0
	v_mfma_f32_16x16x32_bf16 v[28:31], v[210:213], v[178:181], 0
	v_mfma_f32_16x16x32_bf16 v[20:23], v[218:221], v[178:181], 0
	v_mfma_f32_16x16x32_bf16 v[12:15], v[210:213], v[194:197], 0
	v_mfma_f32_16x16x32_bf16 v[8:11], v[218:221], v[194:197], 0
	v_mfma_f32_16x16x32_bf16 v[4:7], v[210:213], v[202:205], 0
	v_mfma_f32_16x16x32_bf16 v[0:3], v[218:221], v[202:205], 0
	v_mfma_f32_16x16x32_bf16 v[44:47], v[214:217], v[174:177], v[44:47]
	v_mfma_f32_16x16x32_bf16 v[36:39], v[222:225], v[174:177], v[36:39]
	v_mfma_f32_16x16x32_bf16 v[28:31], v[214:217], v[188:191], v[28:31]
	v_mfma_f32_16x16x32_bf16 v[20:23], v[222:225], v[188:191], v[20:23]
	v_mfma_f32_16x16x32_bf16 v[12:15], v[214:217], v[198:201], v[12:15]
	v_mfma_f32_16x16x32_bf16 v[8:11], v[222:225], v[198:201], v[8:11]
	v_mfma_f32_16x16x32_bf16 v[4:7], v[214:217], v[206:209], v[4:7]
	v_mfma_f32_16x16x32_bf16 v[0:3], v[222:225], v[206:209], v[0:3]
	s_setprio 0
	s_barrier
	ds_read_b128 v[150:153], v144
	ds_read_b128 v[154:157], v144 offset:1024
	ds_read_b128 v[162:165], v144 offset:2048
	ds_read_b128 v[166:169], v144 offset:3072
	s_add_u32 s0, s38, 0x160000
	s_addc_u32 s1, s39, 0
	s_mov_b32 m0, s44
	ds_read_b128 v[170:173], v142 offset:32768
	ds_read_b128 v[174:177], v142 offset:33792
	ds_read_b128 v[178:181], v142 offset:34816
	ds_read_b128 v[188:191], v142 offset:35840
	ds_read_b128 v[194:197], v142 offset:36864
	ds_read_b128 v[198:201], v142 offset:37888
	ds_read_b128 v[202:205], v142 offset:38912
	global_load_lds_dwordx4 v130, s[0:1]
	s_mov_b32 m0, s45
	ds_read_b128 v[206:209], v142 offset:39936
	global_load_lds_dwordx4 v128, s[0:1]
	s_waitcnt lgkmcnt(8)
	s_barrier
	s_waitcnt lgkmcnt(0)
	s_setprio 1
	v_mfma_f32_16x16x32_bf16 v[124:127], v[150:153], v[170:173], v[124:127]
	v_mfma_f32_16x16x32_bf16 v[120:123], v[162:165], v[170:173], v[120:123]
	v_mfma_f32_16x16x32_bf16 v[116:119], v[150:153], v[178:181], v[116:119]
	v_mfma_f32_16x16x32_bf16 v[112:115], v[162:165], v[178:181], v[112:115]
	v_mfma_f32_16x16x32_bf16 v[104:107], v[150:153], v[194:197], v[104:107]
	v_mfma_f32_16x16x32_bf16 v[96:99], v[162:165], v[194:197], v[96:99]
	v_mfma_f32_16x16x32_bf16 v[88:91], v[150:153], v[202:205], v[88:91]
	v_mfma_f32_16x16x32_bf16 v[80:83], v[162:165], v[202:205], v[80:83]
	v_mfma_f32_16x16x32_bf16 v[124:127], v[154:157], v[174:177], v[124:127]
	v_mfma_f32_16x16x32_bf16 v[120:123], v[166:169], v[174:177], v[120:123]
	v_mfma_f32_16x16x32_bf16 v[116:119], v[154:157], v[188:191], v[116:119]
	v_mfma_f32_16x16x32_bf16 v[112:115], v[166:169], v[188:191], v[112:115]
	v_mfma_f32_16x16x32_bf16 v[104:107], v[154:157], v[198:201], v[104:107]
	v_mfma_f32_16x16x32_bf16 v[96:99], v[166:169], v[198:201], v[96:99]
	v_mfma_f32_16x16x32_bf16 v[88:91], v[154:157], v[206:209], v[88:91]
	v_mfma_f32_16x16x32_bf16 v[80:83], v[166:169], v[206:209], v[80:83]
	s_setprio 0
	s_barrier
	s_add_i32 s4, 0, 0x1c000
	s_add_i32 s0, s64, s35
	v_add_u32_e32 v145, s4, v140
	s_add_i32 m0, s0, 0xffffff80
	ds_read_b128 v[210:213], v145
	ds_read_b128 v[214:217], v145 offset:1024
	ds_read_b128 v[218:221], v145 offset:2048
	global_load_lds_dwordx4 v130, s[36:37] offset:128
	s_add_i32 m0, s0, 0x1f80
	ds_read_b128 v[222:225], v145 offset:3072
	global_load_lds_dwordx4 v128, s[36:37] offset:128
	s_barrier
	s_waitcnt lgkmcnt(0)
	s_setprio 1
	v_mfma_f32_16x16x32_bf16 v[108:111], v[210:213], v[170:173], v[108:111]
	v_mfma_f32_16x16x32_bf16 v[100:103], v[218:221], v[170:173], v[100:103]
	v_mfma_f32_16x16x32_bf16 v[92:95], v[210:213], v[178:181], v[92:95]
	v_mfma_f32_16x16x32_bf16 v[84:87], v[218:221], v[178:181], v[84:87]
	v_mfma_f32_16x16x32_bf16 v[76:79], v[210:213], v[194:197], v[76:79]
	v_mfma_f32_16x16x32_bf16 v[72:75], v[218:221], v[194:197], v[72:75]
	v_mfma_f32_16x16x32_bf16 v[68:71], v[210:213], v[202:205], v[68:71]
	v_mfma_f32_16x16x32_bf16 v[64:67], v[218:221], v[202:205], v[64:67]
	v_mfma_f32_16x16x32_bf16 v[108:111], v[214:217], v[174:177], v[108:111]
	v_mfma_f32_16x16x32_bf16 v[100:103], v[222:225], v[174:177], v[100:103]
	v_mfma_f32_16x16x32_bf16 v[92:95], v[214:217], v[188:191], v[92:95]
	v_mfma_f32_16x16x32_bf16 v[84:87], v[222:225], v[188:191], v[84:87]
	v_mfma_f32_16x16x32_bf16 v[76:79], v[214:217], v[198:201], v[76:79]
	v_mfma_f32_16x16x32_bf16 v[72:75], v[222:225], v[198:201], v[72:75]
	v_mfma_f32_16x16x32_bf16 v[68:71], v[214:217], v[206:209], v[68:71]
	v_mfma_f32_16x16x32_bf16 v[64:67], v[222:225], v[206:209], v[64:67]
	s_setprio 0
	s_add_i32 m0, s56, 0xffffff80
	s_barrier
	ds_read_b128 v[170:173], v142 offset:49152
	ds_read_b128 v[174:177], v142 offset:50176
	ds_read_b128 v[178:181], v142 offset:51200
	ds_read_b128 v[188:191], v142 offset:52224
	ds_read_b128 v[194:197], v142 offset:53248
	ds_read_b128 v[198:201], v142 offset:54272
	ds_read_b128 v[202:205], v142 offset:55296
	global_load_lds_dwordx4 v130, s[38:39] offset:128
	s_add_i32 m0, s57, 0xffffff80
	ds_read_b128 v[206:209], v142 offset:56320
	global_load_lds_dwordx4 v128, s[38:39] offset:128
	s_barrier
; #define PG8_STAGE(bufoff, gbase, voff) do { _Pragma("unroll") for (int _i = 0; _i < 2; ++_i) \
;         __builtin_amdgcn_global_load_lds((const unsigned*)((const char*)(gbase) + (voff)[_i]), (LAS unsigned*)(lds + (bufoff) + ldsw + _i * 8192), 16, 0, 0); } while (0)
; #define PG8_LDA(dst, b, h) do { _Pragma("unroll") for (int m = 0; m < 4; ++m) _Pragma("unroll") for (int k = 0; k < 2; ++k) dst[m][k] = *(const LAS bf16x8*)(lds + PG8_SA(b, h) + aoff + m * 2048 + k * 1024); } while (0)
; #define PG8_LDB(dst, b, h) do { _Pragma("unroll") for (int n = 0; n < 2; ++n) _Pragma("unroll") for (int k = 0; k < 2; ++k) dst[n][k] = *(const LAS bf16x8*)(lds + PG8_SB(b, h) + boff + n * 2048 + k * 1024); } while (0)
; #define PG8_WAIT_V(n) asm volatile("s_waitcnt vmcnt(" #n ")" ::: "memory")
; #define PG8_WAIT_L(n) asm volatile("s_waitcnt lgkmcnt(" #n ")" ::: "memory")
; #define PG8_BAR __builtin_amdgcn_s_barrier()
; #define PG8_SCHED __builtin_amdgcn_sched_barrier(0)
; template <class Epi, class Sched>
; DI void gemm_phase(LAS unsigned char* lds, const Gemm g, const Sched& S, const Epi& E) {
;     ...
;             PG8_LDB(B0, 0, 0); PG8_SCHED; PG8_LDA(At, 0, 0); PG8_STAGE(PG8_SA(1, 1), a1 + hstep, voffA);
;             PG8_WAIT_L(8); PG8_BAR; PG8_WAIT_L(0); PG8_MMA(0, 0, At, B0); PG8_BAR; PG8_SCHED;
;             PG8_LDB(B1, 0, 1); PG8_STAGE(PG8_SB(0, 0), b2, voffB);
;             PG8_BAR; PG8_WAIT_L(0); PG8_MMA(0, 1, At, B1); PG8_BAR;
;             PG8_LDA(At, 0, 1); PG8_STAGE(PG8_SA(0, 0), a2, voffA);
;             PG8_BAR; PG8_WAIT_L(0); PG8_MMA(1, 0, At, B0); PG8_BAR; PG8_SCHED;
;             PG8_STAGE(PG8_SB(0, 1), b2 + hstep, voffB);
;             PG8_WAIT_V(6); PG8_BAR; PG8_MMA(1, 1, At, B1); PG8_BAR;
;             PG8_LDB(B0, 1, 0); PG8_SCHED; PG8_LDA(At, 1, 0); PG8_STAGE(PG8_SA(0, 1), a2 + hstep, voffA);
;             PG8_WAIT_L(8); PG8_BAR; PG8_WAIT_L(0); PG8_MMA(0, 0, At, B0); PG8_BAR; PG8_SCHED;
;             PG8_LDB(B1, 1, 1); PG8_STAGE(PG8_SB(1, 0), b3, voffB);
;             PG8_BAR; PG8_WAIT_L(0); PG8_MMA(0, 1, At, B1); PG8_BAR;
;             PG8_LDA(At, 1, 1); PG8_STAGE(PG8_SA(1, 0), a3, voffA);
;             PG8_BAR; PG8_WAIT_L(0); PG8_MMA(1, 0, At, B0); PG8_BAR; PG8_SCHED;
;             PG8_STAGE(PG8_SB(1, 1), b3 + hstep, voffB);
;             PG8_WAIT_V(6); PG8_BAR; PG8_MMA(1, 1, At, B1); PG8_BAR;
	s_waitcnt lgkmcnt(0)
	s_setprio 1
	v_mfma_f32_16x16x32_bf16 v[60:63], v[150:153], v[170:173], v[60:63]
	v_mfma_f32_16x16x32_bf16 v[56:59], v[162:165], v[170:173], v[56:59]
	v_mfma_f32_16x16x32_bf16 v[52:55], v[150:153], v[178:181], v[52:55]
	v_mfma_f32_16x16x32_bf16 v[48:51], v[162:165], v[178:181], v[48:51]
	v_mfma_f32_16x16x32_bf16 v[40:43], v[150:153], v[194:197], v[40:43]
	v_mfma_f32_16x16x32_bf16 v[32:35], v[162:165], v[194:197], v[32:35]
	v_mfma_f32_16x16x32_bf16 v[24:27], v[150:153], v[202:205], v[24:27]
	v_mfma_f32_16x16x32_bf16 v[16:19], v[162:165], v[202:205], v[16:19]
	v_mfma_f32_16x16x32_bf16 v[60:63], v[154:157], v[174:177], v[60:63]
	v_mfma_f32_16x16x32_bf16 v[56:59], v[166:169], v[174:177], v[56:59]
	v_mfma_f32_16x16x32_bf16 v[52:55], v[154:157], v[188:191], v[52:55]
	v_mfma_f32_16x16x32_bf16 v[48:51], v[166:169], v[188:191], v[48:51]
	v_mfma_f32_16x16x32_bf16 v[40:43], v[154:157], v[198:201], v[40:43]
	v_mfma_f32_16x16x32_bf16 v[32:35], v[166:169], v[198:201], v[32:35]
	v_mfma_f32_16x16x32_bf16 v[24:27], v[154:157], v[206:209], v[24:27]
	v_mfma_f32_16x16x32_bf16 v[16:19], v[166:169], v[206:209], v[16:19]
	s_setprio 0
	s_barrier
	s_add_u32 s0, s36, 0x160080
	s_addc_u32 s1, s37, 0
	s_add_i32 s4, s4, s35
	s_mov_b32 m0, s4
	s_nop 0
	global_load_lds_dwordx4 v130, s[0:1]
	s_add_i32 m0, s4, 0x2000
	s_nop 0
	global_load_lds_dwordx4 v128, s[0:1]
	s_waitcnt vmcnt(6)
	s_barrier
	s_setprio 1
	v_mfma_f32_16x16x32_bf16 v[44:47], v[210:213], v[170:173], v[44:47]
	v_mfma_f32_16x16x32_bf16 v[36:39], v[218:221], v[170:173], v[36:39]
	v_mfma_f32_16x16x32_bf16 v[28:31], v[210:213], v[178:181], v[28:31]
	v_mfma_f32_16x16x32_bf16 v[20:23], v[218:221], v[178:181], v[20:23]
	v_mfma_f32_16x16x32_bf16 v[12:15], v[210:213], v[194:197], v[12:15]
	v_mfma_f32_16x16x32_bf16 v[8:11], v[218:221], v[194:197], v[8:11]
	v_mfma_f32_16x16x32_bf16 v[4:7], v[210:213], v[202:205], v[4:7]
	v_mfma_f32_16x16x32_bf16 v[0:3], v[218:221], v[202:205], v[0:3]
	v_mfma_f32_16x16x32_bf16 v[44:47], v[214:217], v[174:177], v[44:47]
	v_mfma_f32_16x16x32_bf16 v[36:39], v[222:225], v[174:177], v[36:39]
	v_mfma_f32_16x16x32_bf16 v[28:31], v[214:217], v[188:191], v[28:31]
	v_mfma_f32_16x16x32_bf16 v[20:23], v[222:225], v[188:191], v[20:23]
	v_mfma_f32_16x16x32_bf16 v[12:15], v[214:217], v[198:201], v[12:15]
	v_mfma_f32_16x16x32_bf16 v[8:11], v[222:225], v[198:201], v[8:11]
	v_mfma_f32_16x16x32_bf16 v[4:7], v[214:217], v[206:209], v[4:7]
	v_mfma_f32_16x16x32_bf16 v[0:3], v[222:225], v[206:209], v[0:3]
	s_setprio 0
	s_add_i32 s68, s68, 2
	s_add_u32 s8, s8, 0x100
	s_addc_u32 s9, s9, 0
	s_add_u32 s66, s66, 0x100
	s_addc_u32 s67, s67, 0
	s_cmp_gt_u32 s68, 5
	s_barrier
	s_cbranch_scc0 .LBB0_326
	s_branch .Lpeel_done_326
.LBB0_326:
	ds_read_b128 v[150:153], v141
	ds_read_b128 v[154:157], v141 offset:1024
	ds_read_b128 v[162:165], v141 offset:2048
	ds_read_b128 v[166:169], v141 offset:3072
	s_add_u32 s0, s8, 0xffea0080
	s_addc_u32 s1, s9, -1
	s_cmp_eq_u32 s68, 4
	s_cselect_b32 s39, s15, s1
	s_cselect_b32 s38, s17, s0
	s_cselect_b32 s37, s19, s67
	s_cselect_b32 s36, s18, s66
	s_mov_b32 m0, s58
	ds_read_b128 v[170:173], v142
	ds_read_b128 v[174:177], v142 offset:1024
	ds_read_b128 v[178:181], v142 offset:2048
	ds_read_b128 v[188:191], v142 offset:3072
	ds_read_b128 v[194:197], v142 offset:4096
	ds_read_b128 v[198:201], v142 offset:5120
	ds_read_b128 v[202:205], v142 offset:6144
	global_load_lds_dwordx4 v132, s[8:9]
	s_mov_b32 m0, s59
	ds_read_b128 v[206:209], v142 offset:7168
	global_load_lds_dwordx4 v134, s[8:9]
	s_waitcnt lgkmcnt(8)
	s_barrier
	s_waitcnt lgkmcnt(0)
	s_setprio 1
	v_mfma_f32_16x16x32_bf16 v[124:127], v[150:153], v[170:173], v[124:127]
	v_mfma_f32_16x16x32_bf16 v[120:123], v[162:165], v[170:173], v[120:123]
	v_mfma_f32_16x16x32_bf16 v[116:119], v[150:153], v[178:181], v[116:119]
	v_mfma_f32_16x16x32_bf16 v[112:115], v[162:165], v[178:181], v[112:115]
	v_mfma_f32_16x16x32_bf16 v[104:107], v[150:153], v[194:197], v[104:107]
	v_mfma_f32_16x16x32_bf16 v[96:99], v[162:165], v[194:197], v[96:99]
	v_mfma_f32_16x16x32_bf16 v[88:91], v[150:153], v[202:205], v[88:91]
	v_mfma_f32_16x16x32_bf16 v[80:83], v[162:165], v[202:205], v[80:83]
	v_mfma_f32_16x16x32_bf16 v[124:127], v[154:157], v[174:177], v[124:127]
	v_mfma_f32_16x16x32_bf16 v[120:123], v[166:169], v[174:177], v[120:123]
	v_mfma_f32_16x16x32_bf16 v[116:119], v[154:157], v[188:191], v[116:119]
	v_mfma_f32_16x16x32_bf16 v[112:115], v[166:169], v[188:191], v[112:115]
	v_mfma_f32_16x16x32_bf16 v[104:107], v[154:157], v[198:201], v[104:107]
	v_mfma_f32_16x16x32_bf16 v[96:99], v[166:169], v[198:201], v[96:99]
	v_mfma_f32_16x16x32_bf16 v[88:91], v[154:157], v[206:209], v[88:91]
	v_mfma_f32_16x16x32_bf16 v[80:83], v[166:169], v[206:209], v[80:83]
	s_setprio 0
	s_barrier
	s_mov_b32 m0, s60
	ds_read_b128 v[210:213], v143
	ds_read_b128 v[214:217], v143 offset:1024
	ds_read_b128 v[218:221], v143 offset:2048
	global_load_lds_dwordx4 v130, s[36:37]
	s_mov_b32 m0, s61
	ds_read_b128 v[222:225], v143 offset:3072
	global_load_lds_dwordx4 v128, s[36:37]
	s_barrier
; #define PG8_STAGE(bufoff, gbase, voff) do { _Pragma("unroll") for (int _i = 0; _i < 2; ++_i) \
;         __builtin_amdgcn_global_load_lds((const unsigned*)((const char*)(gbase) + (voff)[_i]), (LAS unsigned*)(lds + (bufoff) + ldsw + _i * 8192), 16, 0, 0); } while (0)
; #define PG8_LDA(dst, b, h) do { _Pragma("unroll") for (int m = 0; m < 4; ++m) _Pragma("unroll") for (int k = 0; k < 2; ++k) dst[m][k] = *(const LAS bf16x8*)(lds + PG8_SA(b, h) + aoff + m * 2048 + k * 1024); } while (0)
; #define PG8_LDB(dst, b, h) do { _Pragma("unroll") for (int n = 0; n < 2; ++n) _Pragma("unroll") for (int k = 0; k < 2; ++k) dst[n][k] = *(const LAS bf16x8*)(lds + PG8_SB(b, h) + boff + n * 2048 + k * 1024); } while (0)
; #define PG8_MMA(ai, bj, At, Bt) do { __builtin_amdgcn_s_setprio(1); _Pragma("unroll") for (int m = 0; m < 4; ++m) _Pragma("unroll") for (int n = 0; n < 2; ++n) _Pragma("unroll") for (int k = 0; k < 2; ++k) \
;         acc[ai][bj][m][n] = __builtin_amdgcn_mfma_f32_16x16x32_bf16(Bt[n][k], At[m][k], acc[ai][bj][m][n], 0, 0, 0); __builtin_amdgcn_s_setprio(0); } while (0)
; #define PG8_WAIT_V(n) asm volatile("s_waitcnt vmcnt(" #n ")" ::: "memory")
; #define PG8_WAIT_L(n) asm volatile("s_waitcnt lgkmcnt(" #n ")" ::: "memory")
; #define PG8_BAR __builtin_amdgcn_s_barrier()
; #define PG8_SCHED __builtin_amdgcn_sched_barrier(0)
; template <class Epi, class Sched>
; DI void gemm_phase(LAS unsigned char* lds, const Gemm g, const Sched& S, const Epi& E) {
;     ...
;             PG8_BAR; PG8_WAIT_L(0); PG8_MMA(0, 1, At, B1); PG8_BAR;
;             PG8_LDA(At, 0, 1); PG8_STAGE(PG8_SA(0, 0), a2, voffA);
;             PG8_BAR; PG8_WAIT_L(0); PG8_MMA(1, 0, At, B0); PG8_BAR; PG8_SCHED;
;             PG8_STAGE(PG8_SB(0, 1), b2 + hstep, voffB);
;             PG8_WAIT_V(6); PG8_BAR; PG8_MMA(1, 1, At, B1); PG8_BAR;
;             PG8_LDB(B0, 1, 0); PG8_SCHED; PG8_LDA(At, 1, 0); PG8_STAGE(PG8_SA(0, 1), a2 + hstep, voffA);
;             PG8_WAIT_L(8); PG8_BAR; PG8_WAIT_L(0); PG8_MMA(0, 0, At, B0); PG8_BAR; PG8_SCHED;
	s_waitcnt lgkmcnt(0)
	s_setprio 1
	v_mfma_f32_16x16x32_bf16 v[108:111], v[210:213], v[170:173], v[108:111]
	v_mfma_f32_16x16x32_bf16 v[100:103], v[218:221], v[170:173], v[100:103]
	v_mfma_f32_16x16x32_bf16 v[92:95], v[210:213], v[178:181], v[92:95]
	v_mfma_f32_16x16x32_bf16 v[84:87], v[218:221], v[178:181], v[84:87]
	v_mfma_f32_16x16x32_bf16 v[76:79], v[210:213], v[194:197], v[76:79]
	v_mfma_f32_16x16x32_bf16 v[72:75], v[218:221], v[194:197], v[72:75]
	v_mfma_f32_16x16x32_bf16 v[68:71], v[210:213], v[202:205], v[68:71]
	v_mfma_f32_16x16x32_bf16 v[64:67], v[218:221], v[202:205], v[64:67]
	v_mfma_f32_16x16x32_bf16 v[108:111], v[214:217], v[174:177], v[108:111]
	v_mfma_f32_16x16x32_bf16 v[100:103], v[222:225], v[174:177], v[100:103]
	v_mfma_f32_16x16x32_bf16 v[92:95], v[214:217], v[188:191], v[92:95]
	v_mfma_f32_16x16x32_bf16 v[84:87], v[222:225], v[188:191], v[84:87]
	v_mfma_f32_16x16x32_bf16 v[76:79], v[214:217], v[198:201], v[76:79]
	v_mfma_f32_16x16x32_bf16 v[72:75], v[222:225], v[198:201], v[72:75]
	v_mfma_f32_16x16x32_bf16 v[68:71], v[214:217], v[206:209], v[68:71]
	v_mfma_f32_16x16x32_bf16 v[64:67], v[222:225], v[206:209], v[64:67]
	s_setprio 0
	s_mov_b32 m0, s42
	s_barrier
	ds_read_b128 v[170:173], v142 offset:16384
	ds_read_b128 v[174:177], v142 offset:17408
	ds_read_b128 v[178:181], v142 offset:18432
	ds_read_b128 v[188:191], v142 offset:19456
	ds_read_b128 v[194:197], v142 offset:20480
	ds_read_b128 v[198:201], v142 offset:21504
	ds_read_b128 v[202:205], v142 offset:22528
	global_load_lds_dwordx4 v130, s[38:39]
	s_mov_b32 m0, s43
	ds_read_b128 v[206:209], v142 offset:23552
	global_load_lds_dwordx4 v128, s[38:39]
	s_barrier
	s_waitcnt lgkmcnt(0)
	s_setprio 1
	v_mfma_f32_16x16x32_bf16 v[60:63], v[150:153], v[170:173], v[60:63]
	v_mfma_f32_16x16x32_bf16 v[56:59], v[162:165], v[170:173], v[56:59]
	v_mfma_f32_16x16x32_bf16 v[52:55], v[150:153], v[178:181], v[52:55]
	v_mfma_f32_16x16x32_bf16 v[48:51], v[162:165], v[178:181], v[48:51]
	v_mfma_f32_16x16x32_bf16 v[40:43], v[150:153], v[194:197], v[40:43]
	v_mfma_f32_16x16x32_bf16 v[32:35], v[162:165], v[194:197], v[32:35]
	v_mfma_f32_16x16x32_bf16 v[24:27], v[150:153], v[202:205], v[24:27]
	v_mfma_f32_16x16x32_bf16 v[16:19], v[162:165], v[202:205], v[16:19]
	v_mfma_f32_16x16x32_bf16 v[60:63], v[154:157], v[174:177], v[60:63]
	v_mfma_f32_16x16x32_bf16 v[56:59], v[166:169], v[174:177], v[56:59]
	v_mfma_f32_16x16x32_bf16 v[52:55], v[154:157], v[188:191], v[52:55]
	v_mfma_f32_16x16x32_bf16 v[48:51], v[166:169], v[188:191], v[48:51]
	v_mfma_f32_16x16x32_bf16 v[40:43], v[154:157], v[198:201], v[40:43]
	v_mfma_f32_16x16x32_bf16 v[32:35], v[166:169], v[198:201], v[32:35]
	v_mfma_f32_16x16x32_bf16 v[24:27], v[154:157], v[206:209], v[24:27]
	v_mfma_f32_16x16x32_bf16 v[16:19], v[166:169], v[206:209], v[16:19]
	s_setprio 0
	s_barrier
	s_add_u32 s0, s36, 0x160000
	s_addc_u32 s1, s37, 0
	s_mov_b32 m0, s62
	s_nop 0
	global_load_lds_dwordx4 v130, s[0:1]
	s_mov_b32 m0, s63
	s_nop 0
	global_load_lds_dwordx4 v128, s[0:1]
	s_waitcnt vmcnt(6)
	s_barrier
	s_setprio 1
	v_mfma_f32_16x16x32_bf16 v[44:47], v[210:213], v[170:173], v[44:47]
	v_mfma_f32_16x16x32_bf16 v[36:39], v[218:221], v[170:173], v[36:39]
	v_mfma_f32_16x16x32_bf16 v[28:31], v[210:213], v[178:181], v[28:31]
	v_mfma_f32_16x16x32_bf16 v[20:23], v[218:221], v[178:181], v[20:23]
	v_mfma_f32_16x16x32_bf16 v[12:15], v[210:213], v[194:197], v[12:15]
	v_mfma_f32_16x16x32_bf16 v[8:11], v[218:221], v[194:197], v[8:11]
	v_mfma_f32_16x16x32_bf16 v[4:7], v[210:213], v[202:205], v[4:7]
	v_mfma_f32_16x16x32_bf16 v[0:3], v[218:221], v[202:205], v[0:3]
	v_mfma_f32_16x16x32_bf16 v[44:47], v[214:217], v[174:177], v[44:47]
	v_mfma_f32_16x16x32_bf16 v[36:39], v[222:225], v[174:177], v[36:39]
	v_mfma_f32_16x16x32_bf16 v[28:31], v[214:217], v[188:191], v[28:31]
	v_mfma_f32_16x16x32_bf16 v[20:23], v[222:225], v[188:191], v[20:23]
	v_mfma_f32_16x16x32_bf16 v[12:15], v[214:217], v[198:201], v[12:15]
	v_mfma_f32_16x16x32_bf16 v[8:11], v[222:225], v[198:201], v[8:11]
	v_mfma_f32_16x16x32_bf16 v[4:7], v[214:217], v[206:209], v[4:7]
	v_mfma_f32_16x16x32_bf16 v[0:3], v[222:225], v[206:209], v[0:3]
	s_setprio 0
	s_barrier
	ds_read_b128 v[150:153], v144
	ds_read_b128 v[154:157], v144 offset:1024
	ds_read_b128 v[162:165], v144 offset:2048
	ds_read_b128 v[166:169], v144 offset:3072
	s_add_u32 s0, s38, 0x160000
	s_addc_u32 s1, s39, 0
	s_mov_b32 m0, s44
	ds_read_b128 v[170:173], v142 offset:32768
	ds_read_b128 v[174:177], v142 offset:33792
	ds_read_b128 v[178:181], v142 offset:34816
	ds_read_b128 v[188:191], v142 offset:35840
	ds_read_b128 v[194:197], v142 offset:36864
	ds_read_b128 v[198:201], v142 offset:37888
	ds_read_b128 v[202:205], v142 offset:38912
	global_load_lds_dwordx4 v130, s[0:1]
	s_mov_b32 m0, s45
	ds_read_b128 v[206:209], v142 offset:39936
	global_load_lds_dwordx4 v128, s[0:1]
	s_waitcnt lgkmcnt(8)
	s_barrier
; #define PG8_STAGE(bufoff, gbase, voff) do { _Pragma("unroll") for (int _i = 0; _i < 2; ++_i) \
;         __builtin_amdgcn_global_load_lds((const unsigned*)((const char*)(gbase) + (voff)[_i]), (LAS unsigned*)(lds + (bufoff) + ldsw + _i * 8192), 16, 0, 0); } while (0)
; #define PG8_LDA(dst, b, h) do { _Pragma("unroll") for (int m = 0; m < 4; ++m) _Pragma("unroll") for (int k = 0; k < 2; ++k) dst[m][k] = *(const LAS bf16x8*)(lds + PG8_SA(b, h) + aoff + m * 2048 + k * 1024); } while (0)
; #define PG8_LDB(dst, b, h) do { _Pragma("unroll") for (int n = 0; n < 2; ++n) _Pragma("unroll") for (int k = 0; k < 2; ++k) dst[n][k] = *(const LAS bf16x8*)(lds + PG8_SB(b, h) + boff + n * 2048 + k * 1024); } while (0)
; #define PG8_MMA(ai, bj, At, Bt) do { __builtin_amdgcn_s_setprio(1); _Pragma("unroll") for (int m = 0; m < 4; ++m) _Pragma("unroll") for (int n = 0; n < 2; ++n) _Pragma("unroll") for (int k = 0; k < 2; ++k) \
;         acc[ai][bj][m][n] = __builtin_amdgcn_mfma_f32_16x16x32_bf16(Bt[n][k], At[m][k], acc[ai][bj][m][n], 0, 0, 0); __builtin_amdgcn_s_setprio(0); } while (0)
; #define PG8_WAIT_V(n) asm volatile("s_waitcnt vmcnt(" #n ")" ::: "memory")
; #define PG8_WAIT_L(n) asm volatile("s_waitcnt lgkmcnt(" #n ")" ::: "memory")
; #define PG8_BAR __builtin_amdgcn_s_barrier()
; #define PG8_SCHED __builtin_amdgcn_sched_barrier(0)
; template <class Epi, class Sched>
; DI void gemm_phase(LAS unsigned char* lds, const Gemm g, const Sched& S, const Epi& E) {
;     ...
;             PG8_WAIT_L(8); PG8_BAR; PG8_WAIT_L(0); PG8_MMA(0, 0, At, B0); PG8_BAR; PG8_SCHED;
;             PG8_LDB(B1, 1, 1); PG8_STAGE(PG8_SB(1, 0), b3, voffB);
;             PG8_BAR; PG8_WAIT_L(0); PG8_MMA(0, 1, At, B1); PG8_BAR;
;             PG8_LDA(At, 1, 1); PG8_STAGE(PG8_SA(1, 0), a3, voffA);
;             PG8_BAR; PG8_WAIT_L(0); PG8_MMA(1, 0, At, B0); PG8_BAR; PG8_SCHED;
;             PG8_STAGE(PG8_SB(1, 1), b3 + hstep, voffB);
;             PG8_WAIT_V(6); PG8_BAR; PG8_MMA(1, 1, At, B1); PG8_BAR;
;         }
	s_waitcnt lgkmcnt(0)
	s_setprio 1
	v_mfma_f32_16x16x32_bf16 v[124:127], v[150:153], v[170:173], v[124:127]
	v_mfma_f32_16x16x32_bf16 v[120:123], v[162:165], v[170:173], v[120:123]
	v_mfma_f32_16x16x32_bf16 v[116:119], v[150:153], v[178:181], v[116:119]
	v_mfma_f32_16x16x32_bf16 v[112:115], v[162:165], v[178:181], v[112:115]
	v_mfma_f32_16x16x32_bf16 v[104:107], v[150:153], v[194:197], v[104:107]
	v_mfma_f32_16x16x32_bf16 v[96:99], v[162:165], v[194:197], v[96:99]
	v_mfma_f32_16x16x32_bf16 v[88:91], v[150:153], v[202:205], v[88:91]
	v_mfma_f32_16x16x32_bf16 v[80:83], v[162:165], v[202:205], v[80:83]
	v_mfma_f32_16x16x32_bf16 v[124:127], v[154:157], v[174:177], v[124:127]
	v_mfma_f32_16x16x32_bf16 v[120:123], v[166:169], v[174:177], v[120:123]
	v_mfma_f32_16x16x32_bf16 v[116:119], v[154:157], v[188:191], v[116:119]
	v_mfma_f32_16x16x32_bf16 v[112:115], v[166:169], v[188:191], v[112:115]
	v_mfma_f32_16x16x32_bf16 v[104:107], v[154:157], v[198:201], v[104:107]
	v_mfma_f32_16x16x32_bf16 v[96:99], v[166:169], v[198:201], v[96:99]
	v_mfma_f32_16x16x32_bf16 v[88:91], v[154:157], v[206:209], v[88:91]
	v_mfma_f32_16x16x32_bf16 v[80:83], v[166:169], v[206:209], v[80:83]
	s_setprio 0
	s_barrier
	s_add_i32 s4, 0, 0x1c000
	s_add_i32 s0, s64, s35
	v_add_u32_e32 v145, s4, v140
	s_add_i32 m0, s0, 0xffffff80
	ds_read_b128 v[210:213], v145
	ds_read_b128 v[214:217], v145 offset:1024
	ds_read_b128 v[218:221], v145 offset:2048
	global_load_lds_dwordx4 v130, s[36:37] offset:128
	s_add_i32 m0, s0, 0x1f80
	ds_read_b128 v[222:225], v145 offset:3072
	global_load_lds_dwordx4 v128, s[36:37] offset:128
	s_barrier
	s_waitcnt lgkmcnt(0)
	s_setprio 1
	v_mfma_f32_16x16x32_bf16 v[108:111], v[210:213], v[170:173], v[108:111]
	v_mfma_f32_16x16x32_bf16 v[100:103], v[218:221], v[170:173], v[100:103]
	v_mfma_f32_16x16x32_bf16 v[92:95], v[210:213], v[178:181], v[92:95]
	v_mfma_f32_16x16x32_bf16 v[84:87], v[218:221], v[178:181], v[84:87]
	v_mfma_f32_16x16x32_bf16 v[76:79], v[210:213], v[194:197], v[76:79]
	v_mfma_f32_16x16x32_bf16 v[72:75], v[218:221], v[194:197], v[72:75]
	v_mfma_f32_16x16x32_bf16 v[68:71], v[210:213], v[202:205], v[68:71]
	v_mfma_f32_16x16x32_bf16 v[64:67], v[218:221], v[202:205], v[64:67]
	v_mfma_f32_16x16x32_bf16 v[108:111], v[214:217], v[174:177], v[108:111]
	v_mfma_f32_16x16x32_bf16 v[100:103], v[222:225], v[174:177], v[100:103]
	v_mfma_f32_16x16x32_bf16 v[92:95], v[214:217], v[188:191], v[92:95]
	v_mfma_f32_16x16x32_bf16 v[84:87], v[222:225], v[188:191], v[84:87]
	v_mfma_f32_16x16x32_bf16 v[76:79], v[214:217], v[198:201], v[76:79]
	v_mfma_f32_16x16x32_bf16 v[72:75], v[222:225], v[198:201], v[72:75]
	v_mfma_f32_16x16x32_bf16 v[68:71], v[214:217], v[206:209], v[68:71]
	v_mfma_f32_16x16x32_bf16 v[64:67], v[222:225], v[206:209], v[64:67]
	s_setprio 0
	s_add_i32 m0, s56, 0xffffff80
	s_barrier
	ds_read_b128 v[170:173], v142 offset:49152
	ds_read_b128 v[174:177], v142 offset:50176
	ds_read_b128 v[178:181], v142 offset:51200
	ds_read_b128 v[188:191], v142 offset:52224
	ds_read_b128 v[194:197], v142 offset:53248
	ds_read_b128 v[198:201], v142 offset:54272
	ds_read_b128 v[202:205], v142 offset:55296
	global_load_lds_dwordx4 v130, s[38:39] offset:128
	s_add_i32 m0, s57, 0xffffff80
	ds_read_b128 v[206:209], v142 offset:56320
	global_load_lds_dwordx4 v128, s[38:39] offset:128
	s_barrier
	s_waitcnt lgkmcnt(0)
	s_setprio 1
	v_mfma_f32_16x16x32_bf16 v[60:63], v[150:153], v[170:173], v[60:63]
	v_mfma_f32_16x16x32_bf16 v[56:59], v[162:165], v[170:173], v[56:59]
	v_mfma_f32_16x16x32_bf16 v[52:55], v[150:153], v[178:181], v[52:55]
	v_mfma_f32_16x16x32_bf16 v[48:51], v[162:165], v[178:181], v[48:51]
	v_mfma_f32_16x16x32_bf16 v[40:43], v[150:153], v[194:197], v[40:43]
	v_mfma_f32_16x16x32_bf16 v[32:35], v[162:165], v[194:197], v[32:35]
	v_mfma_f32_16x16x32_bf16 v[24:27], v[150:153], v[202:205], v[24:27]
	v_mfma_f32_16x16x32_bf16 v[16:19], v[162:165], v[202:205], v[16:19]
	v_mfma_f32_16x16x32_bf16 v[60:63], v[154:157], v[174:177], v[60:63]
	v_mfma_f32_16x16x32_bf16 v[56:59], v[166:169], v[174:177], v[56:59]
	v_mfma_f32_16x16x32_bf16 v[52:55], v[154:157], v[188:191], v[52:55]
	v_mfma_f32_16x16x32_bf16 v[48:51], v[166:169], v[188:191], v[48:51]
	v_mfma_f32_16x16x32_bf16 v[40:43], v[154:157], v[198:201], v[40:43]
	v_mfma_f32_16x16x32_bf16 v[32:35], v[166:169], v[198:201], v[32:35]
	v_mfma_f32_16x16x32_bf16 v[24:27], v[154:157], v[206:209], v[24:27]
	v_mfma_f32_16x16x32_bf16 v[16:19], v[166:169], v[206:209], v[16:19]
	s_setprio 0
	s_barrier
	s_add_u32 s0, s36, 0x160080
	s_addc_u32 s1, s37, 0
	s_add_i32 s4, s4, s35
	s_mov_b32 m0, s4
	s_nop 0
	global_load_lds_dwordx4 v130, s[0:1]
	s_add_i32 m0, s4, 0x2000
	s_nop 0
	global_load_lds_dwordx4 v128, s[0:1]
	s_waitcnt vmcnt(6)
	s_barrier
	s_setprio 1
	v_mfma_f32_16x16x32_bf16 v[44:47], v[210:213], v[170:173], v[44:47]
	v_mfma_f32_16x16x32_bf16 v[36:39], v[218:221], v[170:173], v[36:39]
	v_mfma_f32_16x16x32_bf16 v[28:31], v[210:213], v[178:181], v[28:31]
	v_mfma_f32_16x16x32_bf16 v[20:23], v[218:221], v[178:181], v[20:23]
	v_mfma_f32_16x16x32_bf16 v[12:15], v[210:213], v[194:197], v[12:15]
	v_mfma_f32_16x16x32_bf16 v[8:11], v[218:221], v[194:197], v[8:11]
	v_mfma_f32_16x16x32_bf16 v[4:7], v[210:213], v[202:205], v[4:7]
	v_mfma_f32_16x16x32_bf16 v[0:3], v[218:221], v[202:205], v[0:3]
	v_mfma_f32_16x16x32_bf16 v[44:47], v[214:217], v[174:177], v[44:47]
	v_mfma_f32_16x16x32_bf16 v[36:39], v[222:225], v[174:177], v[36:39]
	v_mfma_f32_16x16x32_bf16 v[28:31], v[214:217], v[188:191], v[28:31]
	v_mfma_f32_16x16x32_bf16 v[20:23], v[222:225], v[188:191], v[20:23]
	v_mfma_f32_16x16x32_bf16 v[12:15], v[214:217], v[198:201], v[12:15]
	v_mfma_f32_16x16x32_bf16 v[8:11], v[222:225], v[198:201], v[8:11]
	v_mfma_f32_16x16x32_bf16 v[4:7], v[214:217], v[206:209], v[4:7]
	v_mfma_f32_16x16x32_bf16 v[0:3], v[222:225], v[206:209], v[0:3]
	s_setprio 0
	s_add_i32 s68, s68, 2
	s_add_u32 s8, s8, 0x100
	s_addc_u32 s9, s9, 0
	s_add_u32 s66, s66, 0x100
	s_addc_u32 s67, s67, 0
	s_cmp_gt_u32 s68, 5
	s_barrier
	s_cbranch_scc0 .LBB0_326

;     DI size_t aoff(const Unit& u, size_t tstep) const { return (size_t)u.pm * tstep; }
;     DI size_t boff(const Unit& u, size_t tstep) const { return (size_t)u.pn * tstep; }
;     DI bool next(int i, Unit& u) const { const long L = (long)i * G + c; if (L >= np) return false; u.pm = pmv; u.pn = (int)(L % nN); u.ks = (int)(L / nN); return true; }
;     DI size_t aoff(const Unit& u, size_t) const { return (size_t)u.ks * kbytes; }
;     DI size_t boff(const Unit& u, size_t tstep) const { return (size_t)u.pn * tstep + (size_t)u.ks * kbytes; }
;     DI bool next(int i, Unit& u) const { Unit t; if (!S.next(i / 3, t)) return false; u.pm = t.pm; u.pn = t.pn; u.ks = i % 3; return true; }
;     DI size_t aoff(const Unit& u, size_t tstep) const { return (u.ks < 2 ? offU : offOA) + (size_t)u.pm * tstep; }
; #define PG8_LDA(dst, b, h) do { _Pragma("unroll") for (int m = 0; m < 4; ++m) _Pragma("unroll") for (int k = 0; k < 2; ++k) dst[m][k] = *(const LAS bf16x8*)(lds + PG8_SA(b, h) + aoff + m * 2048 + k * 1024); } while (0)
; template <class Epi, class Sched>
; DI void gemm_phase(LAS unsigned char* lds, const Gemm g, const Sched& S, const Epi& E) {
;     ...
;         const bool has_next = S.next(ui + 1, nxt);
;         const char* nA = has_next ? (const char*)g.A + S.aoff(nxt, tstep) : cA; const char* nB = has_next ? (const char*)g.Bt + S.boff(nxt, tstep) : cB;
;         for (int t = 0; t < nt; t += 2) {
;             if constexpr (Epi::HAS_MID) { if (t == E.mid_t(nt)) { int fr3 = fr, fq3 = fq; asm volatile("" : "+v"(fr3), "+v"(fq3)); E.mid(acc, cur, wr, wc, fr3, fq3); } }
;             const bool last = (t == nt - 2);
;             const char* a1 = cA + (size_t)(t + 1) * kstep;
;             const char* a2 = last ? nA : cA + (size_t)(t + 2) * kstep; const char* b2 = last ? nB : cB + (size_t)(t + 2) * kstep;
;             const char* a3 = a2 + kstep; const char* b3 = b2 + kstep;
;             PG8_LDB(B0, 0, 0); PG8_SCHED; PG8_LDA(At, 0, 0); PG8_STAGE(PG8_SA(1, 1), a1 + hstep, voffA);
;             PG8_WAIT_L(8); PG8_BAR; PG8_WAIT_L(0); PG8_MMA(0, 0, At, B0); PG8_BAR; PG8_SCHED;
;             PG8_LDB(B1, 0, 1); PG8_STAGE(PG8_SB(0, 0), b2, voffB);
;             PG8_BAR; PG8_WAIT_L(0); PG8_MMA(0, 1, At, B1); PG8_BAR;
;             PG8_LDA(At, 0, 1); PG8_STAGE(PG8_SA(0, 0), a2, voffA);
;             PG8_BAR; PG8_WAIT_L(0); PG8_MMA(1, 0, At, B0); PG8_BAR; PG8_SCHED;
.LBB0_526:
	s_ashr_i32 s51, s50, 31
	s_lshl_b64 s[0:1], s[50:51], 20
	s_add_u32 s52, s70, s0
	v_cmp_lt_i64_e32 vcc, s[12:13], v[142:143]
	s_addc_u32 s53, s71, s1
	s_and_b64 s[0:1], vcc, exec
	s_cselect_b32 s14, s53, s9
	s_cselect_b32 s15, s52, s8
	s_ashr_i32 s49, s48, 31
	s_lshl_b64 s[0:1], s[48:49], 20
	s_add_u32 s54, s72, s0
	s_addc_u32 s55, s73, s1
	s_and_b64 s[0:1], vcc, exec
	s_cselect_b32 s16, s55, s11
	s_cselect_b32 s17, s54, s10
	s_add_u32 s8, s8, 0x80080
	s_addc_u32 s9, s9, 0
	s_add_u32 s28, s10, 0x100
	v_mov_b32_e32 v0, 0
	s_addc_u32 s34, s11, 0
	s_mov_b32 s35, -2
	ds_read_b128 v[146:149], v164
	ds_read_b128 v[150:153], v164 offset:1024
	ds_read_b128 v[154:157], v164 offset:2048
	ds_read_b128 v[170:173], v164 offset:3072
	s_add_u32 s0, s8, 0xfff80080
	s_addc_u32 s1, s9, -1
	s_cmp_eq_u32 s35, 28
	s_cselect_b32 s13, s14, s1
	s_cselect_b32 s12, s15, s0
	s_cselect_b32 s11, s16, s34
	s_cselect_b32 s10, s17, s28
	s_add_i32 m0, s59, 0xc000
	ds_read_b128 v[174:177], v165
	ds_read_b128 v[178:181], v165 offset:1024
	ds_read_b128 v[188:191], v165 offset:2048
	ds_read_b128 v[194:197], v165 offset:3072
	ds_read_b128 v[198:201], v165 offset:4096
	ds_read_b128 v[202:205], v165 offset:5120
	ds_read_b128 v[206:209], v165 offset:6144
	global_load_lds_dwordx4 v138, s[8:9]
	s_add_i32 m0, s59, 0xe000
	ds_read_b128 v[210:213], v165 offset:7168
	global_load_lds_dwordx4 v140, s[8:9]
	s_waitcnt lgkmcnt(8)
	s_barrier
	s_waitcnt lgkmcnt(0)
	s_setprio 1
	v_mfma_f32_16x16x32_bf16 v[124:127], v[146:149], v[174:177], 0
	v_mfma_f32_16x16x32_bf16 v[120:123], v[154:157], v[174:177], 0
	v_mfma_f32_16x16x32_bf16 v[108:111], v[146:149], v[188:191], 0
	v_mfma_f32_16x16x32_bf16 v[104:107], v[154:157], v[188:191], 0
	v_mfma_f32_16x16x32_bf16 v[92:95], v[146:149], v[198:201], 0
	v_mfma_f32_16x16x32_bf16 v[88:91], v[154:157], v[198:201], 0
	v_mfma_f32_16x16x32_bf16 v[76:79], v[146:149], v[206:209], 0
	v_mfma_f32_16x16x32_bf16 v[72:75], v[154:157], v[206:209], 0
	v_mfma_f32_16x16x32_bf16 v[124:127], v[150:153], v[178:181], v[124:127]
	v_mfma_f32_16x16x32_bf16 v[120:123], v[170:173], v[178:181], v[120:123]
	v_mfma_f32_16x16x32_bf16 v[108:111], v[150:153], v[194:197], v[108:111]
	v_mfma_f32_16x16x32_bf16 v[104:107], v[170:173], v[194:197], v[104:107]
	v_mfma_f32_16x16x32_bf16 v[92:95], v[150:153], v[202:205], v[92:95]
	v_mfma_f32_16x16x32_bf16 v[88:91], v[170:173], v[202:205], v[88:91]
	v_mfma_f32_16x16x32_bf16 v[76:79], v[150:153], v[210:213], v[76:79]
	v_mfma_f32_16x16x32_bf16 v[72:75], v[170:173], v[210:213], v[72:75]
	s_setprio 0
	s_barrier
	s_add_i32 s0, s47, s74
	s_mov_b32 m0, s0
	ds_read_b128 v[214:217], v166
	ds_read_b128 v[218:221], v166 offset:1024
	ds_read_b128 v[222:225], v166 offset:2048
	global_load_lds_dwordx4 v130, s[10:11]
	s_add_i32 m0, s0, 0x2000
	ds_read_b128 v[226:229], v166 offset:3072
	global_load_lds_dwordx4 v134, s[10:11]
	s_barrier
	s_waitcnt lgkmcnt(0)
	s_setprio 1
	v_mfma_f32_16x16x32_bf16 v[116:119], v[214:217], v[174:177], 0
	v_mfma_f32_16x16x32_bf16 v[112:115], v[222:225], v[174:177], 0
	v_mfma_f32_16x16x32_bf16 v[100:103], v[214:217], v[188:191], 0
	v_mfma_f32_16x16x32_bf16 v[96:99], v[222:225], v[188:191], 0
	v_mfma_f32_16x16x32_bf16 v[84:87], v[214:217], v[198:201], 0
	v_mfma_f32_16x16x32_bf16 v[80:83], v[222:225], v[198:201], 0
	v_mfma_f32_16x16x32_bf16 v[68:71], v[214:217], v[206:209], 0
	v_mfma_f32_16x16x32_bf16 v[64:67], v[222:225], v[206:209], 0
	v_mfma_f32_16x16x32_bf16 v[116:119], v[218:221], v[178:181], v[116:119]
	v_mfma_f32_16x16x32_bf16 v[112:115], v[226:229], v[178:181], v[112:115]
	v_mfma_f32_16x16x32_bf16 v[100:103], v[218:221], v[194:197], v[100:103]
	v_mfma_f32_16x16x32_bf16 v[96:99], v[226:229], v[194:197], v[96:99]
	v_mfma_f32_16x16x32_bf16 v[84:87], v[218:221], v[202:205], v[84:87]
	v_mfma_f32_16x16x32_bf16 v[80:83], v[226:229], v[202:205], v[80:83]
	v_mfma_f32_16x16x32_bf16 v[68:71], v[218:221], v[210:213], v[68:71]
	v_mfma_f32_16x16x32_bf16 v[64:67], v[226:229], v[210:213], v[64:67]
	s_setprio 0
	s_mov_b32 m0, s59
	s_barrier
	ds_read_b128 v[174:177], v165 offset:16384
	ds_read_b128 v[178:181], v165 offset:17408
	ds_read_b128 v[188:191], v165 offset:18432
	ds_read_b128 v[194:197], v165 offset:19456
	ds_read_b128 v[198:201], v165 offset:20480
	ds_read_b128 v[202:205], v165 offset:21504
	ds_read_b128 v[206:209], v165 offset:22528
	global_load_lds_dwordx4 v128, s[12:13]
	s_mov_b32 m0, s75
	ds_read_b128 v[210:213], v165 offset:23552
	global_load_lds_dwordx4 v132, s[12:13]
	s_barrier
	s_waitcnt lgkmcnt(0)
	s_setprio 1
	v_mfma_f32_16x16x32_bf16 v[60:63], v[146:149], v[174:177], 0
	v_mfma_f32_16x16x32_bf16 v[56:59], v[154:157], v[174:177], 0
	v_mfma_f32_16x16x32_bf16 v[44:47], v[146:149], v[188:191], 0
	v_mfma_f32_16x16x32_bf16 v[40:43], v[154:157], v[188:191], 0
	v_mfma_f32_16x16x32_bf16 v[28:31], v[146:149], v[198:201], 0
	v_mfma_f32_16x16x32_bf16 v[24:27], v[154:157], v[198:201], 0
	v_mfma_f32_16x16x32_bf16 v[12:15], v[146:149], v[206:209], 0
	v_mfma_f32_16x16x32_bf16 v[8:11], v[154:157], v[206:209], 0
	v_mfma_f32_16x16x32_bf16 v[60:63], v[150:153], v[178:181], v[60:63]
	v_mfma_f32_16x16x32_bf16 v[56:59], v[170:173], v[178:181], v[56:59]
	v_mfma_f32_16x16x32_bf16 v[44:47], v[150:153], v[194:197], v[44:47]
	v_mfma_f32_16x16x32_bf16 v[40:43], v[170:173], v[194:197], v[40:43]
	v_mfma_f32_16x16x32_bf16 v[28:31], v[150:153], v[202:205], v[28:31]
	v_mfma_f32_16x16x32_bf16 v[24:27], v[170:173], v[202:205], v[24:27]
	v_mfma_f32_16x16x32_bf16 v[12:15], v[150:153], v[210:213], v[12:15]
	v_mfma_f32_16x16x32_bf16 v[8:11], v[170:173], v[210:213], v[8:11]
	s_setprio 0
	s_barrier
; #define PG8_STAGE(bufoff, gbase, voff) do { _Pragma("unroll") for (int _i = 0; _i < 2; ++_i) \
;         __builtin_amdgcn_global_load_lds((const unsigned*)((const char*)(gbase) + (voff)[_i]), (LAS unsigned*)(lds + (bufoff) + ldsw + _i * 8192), 16, 0, 0); } while (0)
; #define PG8_LDA(dst, b, h) do { _Pragma("unroll") for (int m = 0; m < 4; ++m) _Pragma("unroll") for (int k = 0; k < 2; ++k) dst[m][k] = *(const LAS bf16x8*)(lds + PG8_SA(b, h) + aoff + m * 2048 + k * 1024); } while (0)
; #define PG8_LDB(dst, b, h) do { _Pragma("unroll") for (int n = 0; n < 2; ++n) _Pragma("unroll") for (int k = 0; k < 2; ++k) dst[n][k] = *(const LAS bf16x8*)(lds + PG8_SB(b, h) + boff + n * 2048 + k * 1024); } while (0)
; #define PG8_MMA(ai, bj, At, Bt) do { __builtin_amdgcn_s_setprio(1); _Pragma("unroll") for (int m = 0; m < 4; ++m) _Pragma("unroll") for (int n = 0; n < 2; ++n) _Pragma("unroll") for (int k = 0; k < 2; ++k) \
;         acc[ai][bj][m][n] = __builtin_amdgcn_mfma_f32_16x16x32_bf16(Bt[n][k], At[m][k], acc[ai][bj][m][n], 0, 0, 0); __builtin_amdgcn_s_setprio(0); } while (0)
; #define PG8_WAIT_V(n) asm volatile("s_waitcnt vmcnt(" #n ")" ::: "memory")
; #define PG8_WAIT_L(n) asm volatile("s_waitcnt lgkmcnt(" #n ")" ::: "memory")
; #define PG8_BAR __builtin_amdgcn_s_barrier()
; #define PG8_SCHED __builtin_amdgcn_sched_barrier(0)
; template <class Epi, class Sched>
; DI void gemm_phase(LAS unsigned char* lds, const Gemm g, const Sched& S, const Epi& E) {
;     ...
;             PG8_STAGE(PG8_SB(0, 1), b2 + hstep, voffB);
;             PG8_WAIT_V(6); PG8_BAR; PG8_MMA(1, 1, At, B1); PG8_BAR;
;             PG8_LDB(B0, 1, 0); PG8_SCHED; PG8_LDA(At, 1, 0); PG8_STAGE(PG8_SA(0, 1), a2 + hstep, voffA);
;             PG8_WAIT_L(8); PG8_BAR; PG8_WAIT_L(0); PG8_MMA(0, 0, At, B0); PG8_BAR; PG8_SCHED;
;             PG8_LDB(B1, 1, 1); PG8_STAGE(PG8_SB(1, 0), b3, voffB);
;             PG8_BAR; PG8_WAIT_L(0); PG8_MMA(0, 1, At, B1); PG8_BAR;
;             PG8_LDA(At, 1, 1); PG8_STAGE(PG8_SA(1, 0), a3, voffA);
	s_add_u32 s0, s10, 0x80000
	s_addc_u32 s1, s11, 0
	s_add_i32 s4, s87, s74
	s_mov_b32 m0, s4
	s_nop 0
	global_load_lds_dwordx4 v130, s[0:1]
	s_add_i32 m0, s4, 0x2000
	s_nop 0
	global_load_lds_dwordx4 v134, s[0:1]
	s_waitcnt vmcnt(6)
	s_barrier
	s_setprio 1
	v_mfma_f32_16x16x32_bf16 v[52:55], v[214:217], v[174:177], 0
	v_mfma_f32_16x16x32_bf16 v[48:51], v[222:225], v[174:177], 0
	v_mfma_f32_16x16x32_bf16 v[36:39], v[214:217], v[188:191], 0
	v_mfma_f32_16x16x32_bf16 v[32:35], v[222:225], v[188:191], 0
	v_mfma_f32_16x16x32_bf16 v[20:23], v[214:217], v[198:201], 0
	v_mfma_f32_16x16x32_bf16 v[16:19], v[222:225], v[198:201], 0
	v_mfma_f32_16x16x32_bf16 v[4:7], v[214:217], v[206:209], 0
	v_mfma_f32_16x16x32_bf16 v[0:3], v[222:225], v[206:209], 0
	v_mfma_f32_16x16x32_bf16 v[52:55], v[218:221], v[178:181], v[52:55]
	v_mfma_f32_16x16x32_bf16 v[48:51], v[226:229], v[178:181], v[48:51]
	v_mfma_f32_16x16x32_bf16 v[36:39], v[218:221], v[194:197], v[36:39]
	v_mfma_f32_16x16x32_bf16 v[32:35], v[226:229], v[194:197], v[32:35]
	v_mfma_f32_16x16x32_bf16 v[20:23], v[218:221], v[202:205], v[20:23]
	v_mfma_f32_16x16x32_bf16 v[16:19], v[226:229], v[202:205], v[16:19]
	v_mfma_f32_16x16x32_bf16 v[4:7], v[218:221], v[210:213], v[4:7]
	v_mfma_f32_16x16x32_bf16 v[0:3], v[226:229], v[210:213], v[0:3]
	s_setprio 0
	s_add_i32 s4, 0, 0x18000
	v_add_u32_e32 v137, s4, v163
	s_barrier
	ds_read_b128 v[146:149], v137
	ds_read_b128 v[150:153], v137 offset:1024
	ds_read_b128 v[154:157], v137 offset:2048
	ds_read_b128 v[170:173], v137 offset:3072
	s_add_u32 s0, s12, 0x80000
	s_addc_u32 s1, s13, 0
	s_mov_b32 m0, s76
	ds_read_b128 v[174:177], v165 offset:32768
	ds_read_b128 v[178:181], v165 offset:33792
	ds_read_b128 v[188:191], v165 offset:34816
	ds_read_b128 v[194:197], v165 offset:35840
	ds_read_b128 v[198:201], v165 offset:36864
	ds_read_b128 v[202:205], v165 offset:37888
	ds_read_b128 v[206:209], v165 offset:38912
	global_load_lds_dwordx4 v128, s[0:1]
	s_mov_b32 m0, s77
	ds_read_b128 v[210:213], v165 offset:39936
	global_load_lds_dwordx4 v132, s[0:1]
	s_waitcnt lgkmcnt(8)
	s_barrier
	s_waitcnt lgkmcnt(0)
	s_setprio 1
	v_mfma_f32_16x16x32_bf16 v[124:127], v[146:149], v[174:177], v[124:127]
	v_mfma_f32_16x16x32_bf16 v[120:123], v[154:157], v[174:177], v[120:123]
	v_mfma_f32_16x16x32_bf16 v[108:111], v[146:149], v[188:191], v[108:111]
	v_mfma_f32_16x16x32_bf16 v[104:107], v[154:157], v[188:191], v[104:107]
	v_mfma_f32_16x16x32_bf16 v[92:95], v[146:149], v[198:201], v[92:95]
	v_mfma_f32_16x16x32_bf16 v[88:91], v[154:157], v[198:201], v[88:91]
	v_mfma_f32_16x16x32_bf16 v[76:79], v[146:149], v[206:209], v[76:79]
	v_mfma_f32_16x16x32_bf16 v[72:75], v[154:157], v[206:209], v[72:75]
	v_mfma_f32_16x16x32_bf16 v[124:127], v[150:153], v[178:181], v[124:127]
	v_mfma_f32_16x16x32_bf16 v[120:123], v[170:173], v[178:181], v[120:123]
	v_mfma_f32_16x16x32_bf16 v[108:111], v[150:153], v[194:197], v[108:111]
	v_mfma_f32_16x16x32_bf16 v[104:107], v[170:173], v[194:197], v[104:107]
	v_mfma_f32_16x16x32_bf16 v[92:95], v[150:153], v[202:205], v[92:95]
	v_mfma_f32_16x16x32_bf16 v[88:91], v[170:173], v[202:205], v[88:91]
	v_mfma_f32_16x16x32_bf16 v[76:79], v[150:153], v[210:213], v[76:79]
	v_mfma_f32_16x16x32_bf16 v[72:75], v[170:173], v[210:213], v[72:75]
	s_setprio 0
	s_barrier
	s_add_i32 s5, 0, 0x1c000
	s_add_i32 s0, s4, s74
	v_add_u32_e32 v137, s5, v163
	s_add_i32 m0, s0, 0xffffff80
	ds_read_b128 v[214:217], v137
	ds_read_b128 v[218:221], v137 offset:1024
	ds_read_b128 v[222:225], v137 offset:2048
	global_load_lds_dwordx4 v130, s[10:11] offset:128
	s_add_i32 m0, s0, 0x1f80
	ds_read_b128 v[226:229], v137 offset:3072
	global_load_lds_dwordx4 v134, s[10:11] offset:128
	s_barrier
	s_waitcnt lgkmcnt(0)
	s_setprio 1
	v_mfma_f32_16x16x32_bf16 v[116:119], v[214:217], v[174:177], v[116:119]
	v_mfma_f32_16x16x32_bf16 v[112:115], v[222:225], v[174:177], v[112:115]
	v_mfma_f32_16x16x32_bf16 v[100:103], v[214:217], v[188:191], v[100:103]
	v_mfma_f32_16x16x32_bf16 v[96:99], v[222:225], v[188:191], v[96:99]
	v_mfma_f32_16x16x32_bf16 v[84:87], v[214:217], v[198:201], v[84:87]
	v_mfma_f32_16x16x32_bf16 v[80:83], v[222:225], v[198:201], v[80:83]
	v_mfma_f32_16x16x32_bf16 v[68:71], v[214:217], v[206:209], v[68:71]
	v_mfma_f32_16x16x32_bf16 v[64:67], v[222:225], v[206:209], v[64:67]
	v_mfma_f32_16x16x32_bf16 v[116:119], v[218:221], v[178:181], v[116:119]
	v_mfma_f32_16x16x32_bf16 v[112:115], v[226:229], v[178:181], v[112:115]
	v_mfma_f32_16x16x32_bf16 v[100:103], v[218:221], v[194:197], v[100:103]
	v_mfma_f32_16x16x32_bf16 v[96:99], v[226:229], v[194:197], v[96:99]
	v_mfma_f32_16x16x32_bf16 v[84:87], v[218:221], v[202:205], v[84:87]
	v_mfma_f32_16x16x32_bf16 v[80:83], v[226:229], v[202:205], v[80:83]
	v_mfma_f32_16x16x32_bf16 v[68:71], v[218:221], v[210:213], v[68:71]
	v_mfma_f32_16x16x32_bf16 v[64:67], v[226:229], v[210:213], v[64:67]
	s_setprio 0
	s_add_i32 m0, s97, 0xffffff80
	s_barrier
	ds_read_b128 v[174:177], v165 offset:49152
	ds_read_b128 v[178:181], v165 offset:50176
	ds_read_b128 v[188:191], v165 offset:51200
	ds_read_b128 v[194:197], v165 offset:52224
	ds_read_b128 v[198:201], v165 offset:53248
	ds_read_b128 v[202:205], v165 offset:54272
	ds_read_b128 v[206:209], v165 offset:55296
	global_load_lds_dwordx4 v128, s[12:13] offset:128
	s_add_i32 m0, s84, 0xffffff80
	ds_read_b128 v[210:213], v165 offset:56320
	global_load_lds_dwordx4 v132, s[12:13] offset:128
	s_barrier
; #define PG8_STAGE(bufoff, gbase, voff) do { _Pragma("unroll") for (int _i = 0; _i < 2; ++_i) \
;         __builtin_amdgcn_global_load_lds((const unsigned*)((const char*)(gbase) + (voff)[_i]), (LAS unsigned*)(lds + (bufoff) + ldsw + _i * 8192), 16, 0, 0); } while (0)
; #define PG8_LDA(dst, b, h) do { _Pragma("unroll") for (int m = 0; m < 4; ++m) _Pragma("unroll") for (int k = 0; k < 2; ++k) dst[m][k] = *(const LAS bf16x8*)(lds + PG8_SA(b, h) + aoff + m * 2048 + k * 1024); } while (0)
; #define PG8_LDB(dst, b, h) do { _Pragma("unroll") for (int n = 0; n < 2; ++n) _Pragma("unroll") for (int k = 0; k < 2; ++k) dst[n][k] = *(const LAS bf16x8*)(lds + PG8_SB(b, h) + boff + n * 2048 + k * 1024); } while (0)
; #define PG8_WAIT_V(n) asm volatile("s_waitcnt vmcnt(" #n ")" ::: "memory")
; #define PG8_WAIT_L(n) asm volatile("s_waitcnt lgkmcnt(" #n ")" ::: "memory")
; #define PG8_BAR __builtin_amdgcn_s_barrier()
; #define PG8_SCHED __builtin_amdgcn_sched_barrier(0)
; template <class Epi, class Sched>
; DI void gemm_phase(LAS unsigned char* lds, const Gemm g, const Sched& S, const Epi& E) {
;     ...
;             PG8_LDB(B0, 0, 0); PG8_SCHED; PG8_LDA(At, 0, 0); PG8_STAGE(PG8_SA(1, 1), a1 + hstep, voffA);
;             PG8_WAIT_L(8); PG8_BAR; PG8_WAIT_L(0); PG8_MMA(0, 0, At, B0); PG8_BAR; PG8_SCHED;
;             PG8_LDB(B1, 0, 1); PG8_STAGE(PG8_SB(0, 0), b2, voffB);
;             PG8_BAR; PG8_WAIT_L(0); PG8_MMA(0, 1, At, B1); PG8_BAR;
;             PG8_LDA(At, 0, 1); PG8_STAGE(PG8_SA(0, 0), a2, voffA);
;             PG8_BAR; PG8_WAIT_L(0); PG8_MMA(1, 0, At, B0); PG8_BAR; PG8_SCHED;
;             PG8_STAGE(PG8_SB(0, 1), b2 + hstep, voffB);
;             PG8_WAIT_V(6); PG8_BAR; PG8_MMA(1, 1, At, B1); PG8_BAR;
;             PG8_LDB(B0, 1, 0); PG8_SCHED; PG8_LDA(At, 1, 0); PG8_STAGE(PG8_SA(0, 1), a2 + hstep, voffA);
;             PG8_WAIT_L(8); PG8_BAR; PG8_WAIT_L(0); PG8_MMA(0, 0, At, B0); PG8_BAR; PG8_SCHED;
;             PG8_LDB(B1, 1, 1); PG8_STAGE(PG8_SB(1, 0), b3, voffB);
;             PG8_BAR; PG8_WAIT_L(0); PG8_MMA(0, 1, At, B1); PG8_BAR;
;             PG8_LDA(At, 1, 1); PG8_STAGE(PG8_SA(1, 0), a3, voffA);
;             PG8_BAR; PG8_WAIT_L(0); PG8_MMA(1, 0, At, B0); PG8_BAR; PG8_SCHED;
;             PG8_STAGE(PG8_SB(1, 1), b3 + hstep, voffB);
;             PG8_WAIT_V(6); PG8_BAR; PG8_MMA(1, 1, At, B1); PG8_BAR;
	s_waitcnt lgkmcnt(0)
	s_setprio 1
	v_mfma_f32_16x16x32_bf16 v[60:63], v[146:149], v[174:177], v[60:63]
	v_mfma_f32_16x16x32_bf16 v[56:59], v[154:157], v[174:177], v[56:59]
	v_mfma_f32_16x16x32_bf16 v[44:47], v[146:149], v[188:191], v[44:47]
	v_mfma_f32_16x16x32_bf16 v[40:43], v[154:157], v[188:191], v[40:43]
	v_mfma_f32_16x16x32_bf16 v[28:31], v[146:149], v[198:201], v[28:31]
	v_mfma_f32_16x16x32_bf16 v[24:27], v[154:157], v[198:201], v[24:27]
	v_mfma_f32_16x16x32_bf16 v[12:15], v[146:149], v[206:209], v[12:15]
	v_mfma_f32_16x16x32_bf16 v[8:11], v[154:157], v[206:209], v[8:11]
	v_mfma_f32_16x16x32_bf16 v[60:63], v[150:153], v[178:181], v[60:63]
	v_mfma_f32_16x16x32_bf16 v[56:59], v[170:173], v[178:181], v[56:59]
	v_mfma_f32_16x16x32_bf16 v[44:47], v[150:153], v[194:197], v[44:47]
	v_mfma_f32_16x16x32_bf16 v[40:43], v[170:173], v[194:197], v[40:43]
	v_mfma_f32_16x16x32_bf16 v[28:31], v[150:153], v[202:205], v[28:31]
	v_mfma_f32_16x16x32_bf16 v[24:27], v[170:173], v[202:205], v[24:27]
	v_mfma_f32_16x16x32_bf16 v[12:15], v[150:153], v[210:213], v[12:15]
	v_mfma_f32_16x16x32_bf16 v[8:11], v[170:173], v[210:213], v[8:11]
	s_setprio 0
	s_barrier
	s_add_u32 s0, s10, 0x80080
	s_addc_u32 s1, s11, 0
	s_add_i32 s4, s5, s74
	s_mov_b32 m0, s4
	s_nop 0
	global_load_lds_dwordx4 v130, s[0:1]
	v_lshl_add_u64 v[146:147], s[0:1], 0, v[134:135]
	s_add_i32 m0, s4, 0x2000
	s_nop 0
	global_load_lds_dwordx4 v134, s[0:1]
	s_waitcnt vmcnt(6)
	s_barrier
	s_setprio 1
	v_mfma_f32_16x16x32_bf16 v[52:55], v[214:217], v[174:177], v[52:55]
	v_mfma_f32_16x16x32_bf16 v[48:51], v[222:225], v[174:177], v[48:51]
	v_mfma_f32_16x16x32_bf16 v[36:39], v[214:217], v[188:191], v[36:39]
	v_mfma_f32_16x16x32_bf16 v[32:35], v[222:225], v[188:191], v[32:35]
	v_mfma_f32_16x16x32_bf16 v[20:23], v[214:217], v[198:201], v[20:23]
	v_mfma_f32_16x16x32_bf16 v[16:19], v[222:225], v[198:201], v[16:19]
	v_mfma_f32_16x16x32_bf16 v[4:7], v[214:217], v[206:209], v[4:7]
	v_mfma_f32_16x16x32_bf16 v[0:3], v[222:225], v[206:209], v[0:3]
	v_mfma_f32_16x16x32_bf16 v[52:55], v[218:221], v[178:181], v[52:55]
	v_mfma_f32_16x16x32_bf16 v[48:51], v[226:229], v[178:181], v[48:51]
	v_mfma_f32_16x16x32_bf16 v[36:39], v[218:221], v[194:197], v[36:39]
	v_mfma_f32_16x16x32_bf16 v[32:35], v[226:229], v[194:197], v[32:35]
	v_mfma_f32_16x16x32_bf16 v[20:23], v[218:221], v[202:205], v[20:23]
	v_mfma_f32_16x16x32_bf16 v[16:19], v[226:229], v[202:205], v[16:19]
	v_mfma_f32_16x16x32_bf16 v[4:7], v[218:221], v[210:213], v[4:7]
	v_mfma_f32_16x16x32_bf16 v[0:3], v[226:229], v[210:213], v[0:3]
	s_setprio 0
	s_add_i32 s35, s35, 2
	s_add_u32 s8, s8, 0x100
	s_addc_u32 s9, s9, 0
	s_add_u32 s28, s28, 0x100
	s_addc_u32 s34, s34, 0
	s_cmp_gt_u32 s35, 29
	s_barrier
	s_cbranch_scc0 .LBB0_527
	s_branch .Lpeel_done_527
.LBB0_527:
	ds_read_b128 v[146:149], v164
	ds_read_b128 v[150:153], v164 offset:1024
	ds_read_b128 v[154:157], v164 offset:2048
	ds_read_b128 v[170:173], v164 offset:3072
	s_add_u32 s0, s8, 0xfff80080
	s_addc_u32 s1, s9, -1
	s_cmp_eq_u32 s35, 28
	s_cselect_b32 s13, s14, s1
	s_cselect_b32 s12, s15, s0
	s_cselect_b32 s11, s16, s34
	s_cselect_b32 s10, s17, s28
	s_add_i32 m0, s59, 0xc000
	ds_read_b128 v[174:177], v165
	ds_read_b128 v[178:181], v165 offset:1024
	ds_read_b128 v[188:191], v165 offset:2048
	ds_read_b128 v[194:197], v165 offset:3072
	ds_read_b128 v[198:201], v165 offset:4096
	ds_read_b128 v[202:205], v165 offset:5120
	ds_read_b128 v[206:209], v165 offset:6144
	global_load_lds_dwordx4 v138, s[8:9]
	s_add_i32 m0, s59, 0xe000
	ds_read_b128 v[210:213], v165 offset:7168
	global_load_lds_dwordx4 v140, s[8:9]
	s_waitcnt lgkmcnt(8)
	s_barrier
	s_waitcnt lgkmcnt(0)
	s_setprio 1
	v_mfma_f32_16x16x32_bf16 v[124:127], v[146:149], v[174:177], v[124:127]
	v_mfma_f32_16x16x32_bf16 v[120:123], v[154:157], v[174:177], v[120:123]
	v_mfma_f32_16x16x32_bf16 v[108:111], v[146:149], v[188:191], v[108:111]
	v_mfma_f32_16x16x32_bf16 v[104:107], v[154:157], v[188:191], v[104:107]
	v_mfma_f32_16x16x32_bf16 v[92:95], v[146:149], v[198:201], v[92:95]
	v_mfma_f32_16x16x32_bf16 v[88:91], v[154:157], v[198:201], v[88:91]
	v_mfma_f32_16x16x32_bf16 v[76:79], v[146:149], v[206:209], v[76:79]
	v_mfma_f32_16x16x32_bf16 v[72:75], v[154:157], v[206:209], v[72:75]
	v_mfma_f32_16x16x32_bf16 v[124:127], v[150:153], v[178:181], v[124:127]
	v_mfma_f32_16x16x32_bf16 v[120:123], v[170:173], v[178:181], v[120:123]
	v_mfma_f32_16x16x32_bf16 v[108:111], v[150:153], v[194:197], v[108:111]
	v_mfma_f32_16x16x32_bf16 v[104:107], v[170:173], v[194:197], v[104:107]
	v_mfma_f32_16x16x32_bf16 v[92:95], v[150:153], v[202:205], v[92:95]
	v_mfma_f32_16x16x32_bf16 v[88:91], v[170:173], v[202:205], v[88:91]
	v_mfma_f32_16x16x32_bf16 v[76:79], v[150:153], v[210:213], v[76:79]
	v_mfma_f32_16x16x32_bf16 v[72:75], v[170:173], v[210:213], v[72:75]
	s_setprio 0
	s_barrier
	s_add_i32 s0, s47, s74
	s_mov_b32 m0, s0
	ds_read_b128 v[214:217], v166
	ds_read_b128 v[218:221], v166 offset:1024
	ds_read_b128 v[222:225], v166 offset:2048
	global_load_lds_dwordx4 v130, s[10:11]
	s_add_i32 m0, s0, 0x2000
	ds_read_b128 v[226:229], v166 offset:3072
	global_load_lds_dwordx4 v134, s[10:11]
	s_barrier
; #define PG8_STAGE(bufoff, gbase, voff) do { _Pragma("unroll") for (int _i = 0; _i < 2; ++_i) \
;         __builtin_amdgcn_global_load_lds((const unsigned*)((const char*)(gbase) + (voff)[_i]), (LAS unsigned*)(lds + (bufoff) + ldsw + _i * 8192), 16, 0, 0); } while (0)
; #define PG8_LDA(dst, b, h) do { _Pragma("unroll") for (int m = 0; m < 4; ++m) _Pragma("unroll") for (int k = 0; k < 2; ++k) dst[m][k] = *(const LAS bf16x8*)(lds + PG8_SA(b, h) + aoff + m * 2048 + k * 1024); } while (0)
; #define PG8_LDB(dst, b, h) do { _Pragma("unroll") for (int n = 0; n < 2; ++n) _Pragma("unroll") for (int k = 0; k < 2; ++k) dst[n][k] = *(const LAS bf16x8*)(lds + PG8_SB(b, h) + boff + n * 2048 + k * 1024); } while (0)
; #define PG8_MMA(ai, bj, At, Bt) do { __builtin_amdgcn_s_setprio(1); _Pragma("unroll") for (int m = 0; m < 4; ++m) _Pragma("unroll") for (int n = 0; n < 2; ++n) _Pragma("unroll") for (int k = 0; k < 2; ++k) \
;         acc[ai][bj][m][n] = __builtin_amdgcn_mfma_f32_16x16x32_bf16(Bt[n][k], At[m][k], acc[ai][bj][m][n], 0, 0, 0); __builtin_amdgcn_s_setprio(0); } while (0)
; #define PG8_WAIT_V(n) asm volatile("s_waitcnt vmcnt(" #n ")" ::: "memory")
; #define PG8_WAIT_L(n) asm volatile("s_waitcnt lgkmcnt(" #n ")" ::: "memory")
; #define PG8_BAR __builtin_amdgcn_s_barrier()
; #define PG8_SCHED __builtin_amdgcn_sched_barrier(0)
; template <class Epi, class Sched>
; DI void gemm_phase(LAS unsigned char* lds, const Gemm g, const Sched& S, const Epi& E) {
;     ...
;             PG8_BAR; PG8_WAIT_L(0); PG8_MMA(0, 1, At, B1); PG8_BAR;
;             PG8_LDA(At, 0, 1); PG8_STAGE(PG8_SA(0, 0), a2, voffA);
;             PG8_BAR; PG8_WAIT_L(0); PG8_MMA(1, 0, At, B0); PG8_BAR; PG8_SCHED;
;             PG8_STAGE(PG8_SB(0, 1), b2 + hstep, voffB);
;             PG8_WAIT_V(6); PG8_BAR; PG8_MMA(1, 1, At, B1); PG8_BAR;
;             PG8_LDB(B0, 1, 0); PG8_SCHED; PG8_LDA(At, 1, 0); PG8_STAGE(PG8_SA(0, 1), a2 + hstep, voffA);
;             PG8_WAIT_L(8); PG8_BAR; PG8_WAIT_L(0); PG8_MMA(0, 0, At, B0); PG8_BAR; PG8_SCHED;
	s_waitcnt lgkmcnt(0)
	s_setprio 1
	v_mfma_f32_16x16x32_bf16 v[116:119], v[214:217], v[174:177], v[116:119]
	v_mfma_f32_16x16x32_bf16 v[112:115], v[222:225], v[174:177], v[112:115]
	v_mfma_f32_16x16x32_bf16 v[100:103], v[214:217], v[188:191], v[100:103]
	v_mfma_f32_16x16x32_bf16 v[96:99], v[222:225], v[188:191], v[96:99]
	v_mfma_f32_16x16x32_bf16 v[84:87], v[214:217], v[198:201], v[84:87]
	v_mfma_f32_16x16x32_bf16 v[80:83], v[222:225], v[198:201], v[80:83]
	v_mfma_f32_16x16x32_bf16 v[68:71], v[214:217], v[206:209], v[68:71]
	v_mfma_f32_16x16x32_bf16 v[64:67], v[222:225], v[206:209], v[64:67]
	v_mfma_f32_16x16x32_bf16 v[116:119], v[218:221], v[178:181], v[116:119]
	v_mfma_f32_16x16x32_bf16 v[112:115], v[226:229], v[178:181], v[112:115]
	v_mfma_f32_16x16x32_bf16 v[100:103], v[218:221], v[194:197], v[100:103]
	v_mfma_f32_16x16x32_bf16 v[96:99], v[226:229], v[194:197], v[96:99]
	v_mfma_f32_16x16x32_bf16 v[84:87], v[218:221], v[202:205], v[84:87]
	v_mfma_f32_16x16x32_bf16 v[80:83], v[226:229], v[202:205], v[80:83]
	v_mfma_f32_16x16x32_bf16 v[68:71], v[218:221], v[210:213], v[68:71]
	v_mfma_f32_16x16x32_bf16 v[64:67], v[226:229], v[210:213], v[64:67]
	s_setprio 0
	s_mov_b32 m0, s59
	s_barrier
	ds_read_b128 v[174:177], v165 offset:16384
	ds_read_b128 v[178:181], v165 offset:17408
	ds_read_b128 v[188:191], v165 offset:18432
	ds_read_b128 v[194:197], v165 offset:19456
	ds_read_b128 v[198:201], v165 offset:20480
	ds_read_b128 v[202:205], v165 offset:21504
	ds_read_b128 v[206:209], v165 offset:22528
	global_load_lds_dwordx4 v128, s[12:13]
	s_mov_b32 m0, s75
	ds_read_b128 v[210:213], v165 offset:23552
	global_load_lds_dwordx4 v132, s[12:13]
	s_barrier
	s_waitcnt lgkmcnt(0)
	s_setprio 1
	v_mfma_f32_16x16x32_bf16 v[60:63], v[146:149], v[174:177], v[60:63]
	v_mfma_f32_16x16x32_bf16 v[56:59], v[154:157], v[174:177], v[56:59]
	v_mfma_f32_16x16x32_bf16 v[44:47], v[146:149], v[188:191], v[44:47]
	v_mfma_f32_16x16x32_bf16 v[40:43], v[154:157], v[188:191], v[40:43]
	v_mfma_f32_16x16x32_bf16 v[28:31], v[146:149], v[198:201], v[28:31]
	v_mfma_f32_16x16x32_bf16 v[24:27], v[154:157], v[198:201], v[24:27]
	v_mfma_f32_16x16x32_bf16 v[12:15], v[146:149], v[206:209], v[12:15]
	v_mfma_f32_16x16x32_bf16 v[8:11], v[154:157], v[206:209], v[8:11]
	v_mfma_f32_16x16x32_bf16 v[60:63], v[150:153], v[178:181], v[60:63]
	v_mfma_f32_16x16x32_bf16 v[56:59], v[170:173], v[178:181], v[56:59]
	v_mfma_f32_16x16x32_bf16 v[44:47], v[150:153], v[194:197], v[44:47]
	v_mfma_f32_16x16x32_bf16 v[40:43], v[170:173], v[194:197], v[40:43]
	v_mfma_f32_16x16x32_bf16 v[28:31], v[150:153], v[202:205], v[28:31]
	v_mfma_f32_16x16x32_bf16 v[24:27], v[170:173], v[202:205], v[24:27]
	v_mfma_f32_16x16x32_bf16 v[12:15], v[150:153], v[210:213], v[12:15]
	v_mfma_f32_16x16x32_bf16 v[8:11], v[170:173], v[210:213], v[8:11]
	s_setprio 0
	s_barrier
	s_add_u32 s0, s10, 0x80000
	s_addc_u32 s1, s11, 0
	s_add_i32 s4, s87, s74
	s_mov_b32 m0, s4
	s_nop 0
	global_load_lds_dwordx4 v130, s[0:1]
	s_add_i32 m0, s4, 0x2000
	s_nop 0
	global_load_lds_dwordx4 v134, s[0:1]
	s_waitcnt vmcnt(6)
	s_barrier
	s_setprio 1
	v_mfma_f32_16x16x32_bf16 v[52:55], v[214:217], v[174:177], v[52:55]
	v_mfma_f32_16x16x32_bf16 v[48:51], v[222:225], v[174:177], v[48:51]
	v_mfma_f32_16x16x32_bf16 v[36:39], v[214:217], v[188:191], v[36:39]
	v_mfma_f32_16x16x32_bf16 v[32:35], v[222:225], v[188:191], v[32:35]
	v_mfma_f32_16x16x32_bf16 v[20:23], v[214:217], v[198:201], v[20:23]
	v_mfma_f32_16x16x32_bf16 v[16:19], v[222:225], v[198:201], v[16:19]
	v_mfma_f32_16x16x32_bf16 v[4:7], v[214:217], v[206:209], v[4:7]
	v_mfma_f32_16x16x32_bf16 v[0:3], v[222:225], v[206:209], v[0:3]
	v_mfma_f32_16x16x32_bf16 v[52:55], v[218:221], v[178:181], v[52:55]
	v_mfma_f32_16x16x32_bf16 v[48:51], v[226:229], v[178:181], v[48:51]
	v_mfma_f32_16x16x32_bf16 v[36:39], v[218:221], v[194:197], v[36:39]
	v_mfma_f32_16x16x32_bf16 v[32:35], v[226:229], v[194:197], v[32:35]
	v_mfma_f32_16x16x32_bf16 v[20:23], v[218:221], v[202:205], v[20:23]
	v_mfma_f32_16x16x32_bf16 v[16:19], v[226:229], v[202:205], v[16:19]
	v_mfma_f32_16x16x32_bf16 v[4:7], v[218:221], v[210:213], v[4:7]
	v_mfma_f32_16x16x32_bf16 v[0:3], v[226:229], v[210:213], v[0:3]
	s_setprio 0
	s_add_i32 s4, 0, 0x18000
	v_add_u32_e32 v137, s4, v163
	s_barrier
	ds_read_b128 v[146:149], v137
	ds_read_b128 v[150:153], v137 offset:1024
	ds_read_b128 v[154:157], v137 offset:2048
	ds_read_b128 v[170:173], v137 offset:3072
	s_add_u32 s0, s12, 0x80000
	s_addc_u32 s1, s13, 0
	s_mov_b32 m0, s76
	ds_read_b128 v[174:177], v165 offset:32768
	ds_read_b128 v[178:181], v165 offset:33792
	ds_read_b128 v[188:191], v165 offset:34816
	ds_read_b128 v[194:197], v165 offset:35840
	ds_read_b128 v[198:201], v165 offset:36864
	ds_read_b128 v[202:205], v165 offset:37888
	ds_read_b128 v[206:209], v165 offset:38912
	global_load_lds_dwordx4 v128, s[0:1]
	s_mov_b32 m0, s77
	ds_read_b128 v[210:213], v165 offset:39936
	global_load_lds_dwordx4 v132, s[0:1]
	s_waitcnt lgkmcnt(8)
	s_barrier
; #define PG8_STAGE(bufoff, gbase, voff) do { _Pragma("unroll") for (int _i = 0; _i < 2; ++_i) \
;         __builtin_amdgcn_global_load_lds((const unsigned*)((const char*)(gbase) + (voff)[_i]), (LAS unsigned*)(lds + (bufoff) + ldsw + _i * 8192), 16, 0, 0); } while (0)
; #define PG8_LDA(dst, b, h) do { _Pragma("unroll") for (int m = 0; m < 4; ++m) _Pragma("unroll") for (int k = 0; k < 2; ++k) dst[m][k] = *(const LAS bf16x8*)(lds + PG8_SA(b, h) + aoff + m * 2048 + k * 1024); } while (0)
; #define PG8_LDB(dst, b, h) do { _Pragma("unroll") for (int n = 0; n < 2; ++n) _Pragma("unroll") for (int k = 0; k < 2; ++k) dst[n][k] = *(const LAS bf16x8*)(lds + PG8_SB(b, h) + boff + n * 2048 + k * 1024); } while (0)
; #define PG8_MMA(ai, bj, At, Bt) do { __builtin_amdgcn_s_setprio(1); _Pragma("unroll") for (int m = 0; m < 4; ++m) _Pragma("unroll") for (int n = 0; n < 2; ++n) _Pragma("unroll") for (int k = 0; k < 2; ++k) \
;         acc[ai][bj][m][n] = __builtin_amdgcn_mfma_f32_16x16x32_bf16(Bt[n][k], At[m][k], acc[ai][bj][m][n], 0, 0, 0); __builtin_amdgcn_s_setprio(0); } while (0)
; #define PG8_WAIT_V(n) asm volatile("s_waitcnt vmcnt(" #n ")" ::: "memory")
; #define PG8_WAIT_L(n) asm volatile("s_waitcnt lgkmcnt(" #n ")" ::: "memory")
; #define PG8_BAR __builtin_amdgcn_s_barrier()
; #define PG8_SCHED __builtin_amdgcn_sched_barrier(0)
; template <class Epi, class Sched>
; DI void gemm_phase(LAS unsigned char* lds, const Gemm g, const Sched& S, const Epi& E) {
;     ...
;             PG8_WAIT_L(8); PG8_BAR; PG8_WAIT_L(0); PG8_MMA(0, 0, At, B0); PG8_BAR; PG8_SCHED;
;             PG8_LDB(B1, 1, 1); PG8_STAGE(PG8_SB(1, 0), b3, voffB);
;             PG8_BAR; PG8_WAIT_L(0); PG8_MMA(0, 1, At, B1); PG8_BAR;
;             PG8_LDA(At, 1, 1); PG8_STAGE(PG8_SA(1, 0), a3, voffA);
;             PG8_BAR; PG8_WAIT_L(0); PG8_MMA(1, 0, At, B0); PG8_BAR; PG8_SCHED;
;             PG8_STAGE(PG8_SB(1, 1), b3 + hstep, voffB);
;             PG8_WAIT_V(6); PG8_BAR; PG8_MMA(1, 1, At, B1); PG8_BAR;
;         }
	s_waitcnt lgkmcnt(0)
	s_setprio 1
	v_mfma_f32_16x16x32_bf16 v[124:127], v[146:149], v[174:177], v[124:127]
	v_mfma_f32_16x16x32_bf16 v[120:123], v[154:157], v[174:177], v[120:123]
	v_mfma_f32_16x16x32_bf16 v[108:111], v[146:149], v[188:191], v[108:111]
	v_mfma_f32_16x16x32_bf16 v[104:107], v[154:157], v[188:191], v[104:107]
	v_mfma_f32_16x16x32_bf16 v[92:95], v[146:149], v[198:201], v[92:95]
	v_mfma_f32_16x16x32_bf16 v[88:91], v[154:157], v[198:201], v[88:91]
	v_mfma_f32_16x16x32_bf16 v[76:79], v[146:149], v[206:209], v[76:79]
	v_mfma_f32_16x16x32_bf16 v[72:75], v[154:157], v[206:209], v[72:75]
	v_mfma_f32_16x16x32_bf16 v[124:127], v[150:153], v[178:181], v[124:127]
	v_mfma_f32_16x16x32_bf16 v[120:123], v[170:173], v[178:181], v[120:123]
	v_mfma_f32_16x16x32_bf16 v[108:111], v[150:153], v[194:197], v[108:111]
	v_mfma_f32_16x16x32_bf16 v[104:107], v[170:173], v[194:197], v[104:107]
	v_mfma_f32_16x16x32_bf16 v[92:95], v[150:153], v[202:205], v[92:95]
	v_mfma_f32_16x16x32_bf16 v[88:91], v[170:173], v[202:205], v[88:91]
	v_mfma_f32_16x16x32_bf16 v[76:79], v[150:153], v[210:213], v[76:79]
	v_mfma_f32_16x16x32_bf16 v[72:75], v[170:173], v[210:213], v[72:75]
	s_setprio 0
	s_barrier
	s_add_i32 s5, 0, 0x1c000
	s_add_i32 s0, s4, s74
	v_add_u32_e32 v137, s5, v163
	s_add_i32 m0, s0, 0xffffff80
	ds_read_b128 v[214:217], v137
	ds_read_b128 v[218:221], v137 offset:1024
	ds_read_b128 v[222:225], v137 offset:2048
	global_load_lds_dwordx4 v130, s[10:11] offset:128
	s_add_i32 m0, s0, 0x1f80
	ds_read_b128 v[226:229], v137 offset:3072
	global_load_lds_dwordx4 v134, s[10:11] offset:128
	s_barrier
	s_waitcnt lgkmcnt(0)
	s_setprio 1
	v_mfma_f32_16x16x32_bf16 v[116:119], v[214:217], v[174:177], v[116:119]
	v_mfma_f32_16x16x32_bf16 v[112:115], v[222:225], v[174:177], v[112:115]
	v_mfma_f32_16x16x32_bf16 v[100:103], v[214:217], v[188:191], v[100:103]
	v_mfma_f32_16x16x32_bf16 v[96:99], v[222:225], v[188:191], v[96:99]
	v_mfma_f32_16x16x32_bf16 v[84:87], v[214:217], v[198:201], v[84:87]
	v_mfma_f32_16x16x32_bf16 v[80:83], v[222:225], v[198:201], v[80:83]
	v_mfma_f32_16x16x32_bf16 v[68:71], v[214:217], v[206:209], v[68:71]
	v_mfma_f32_16x16x32_bf16 v[64:67], v[222:225], v[206:209], v[64:67]
	v_mfma_f32_16x16x32_bf16 v[116:119], v[218:221], v[178:181], v[116:119]
	v_mfma_f32_16x16x32_bf16 v[112:115], v[226:229], v[178:181], v[112:115]
	v_mfma_f32_16x16x32_bf16 v[100:103], v[218:221], v[194:197], v[100:103]
	v_mfma_f32_16x16x32_bf16 v[96:99], v[226:229], v[194:197], v[96:99]
	v_mfma_f32_16x16x32_bf16 v[84:87], v[218:221], v[202:205], v[84:87]
	v_mfma_f32_16x16x32_bf16 v[80:83], v[226:229], v[202:205], v[80:83]
	v_mfma_f32_16x16x32_bf16 v[68:71], v[218:221], v[210:213], v[68:71]
	v_mfma_f32_16x16x32_bf16 v[64:67], v[226:229], v[210:213], v[64:67]
	s_setprio 0
	s_add_i32 m0, s97, 0xffffff80
	s_barrier
	ds_read_b128 v[174:177], v165 offset:49152
	ds_read_b128 v[178:181], v165 offset:50176
	ds_read_b128 v[188:191], v165 offset:51200
	ds_read_b128 v[194:197], v165 offset:52224
	ds_read_b128 v[198:201], v165 offset:53248
	ds_read_b128 v[202:205], v165 offset:54272
	ds_read_b128 v[206:209], v165 offset:55296
	global_load_lds_dwordx4 v128, s[12:13] offset:128
	s_add_i32 m0, s84, 0xffffff80
	ds_read_b128 v[210:213], v165 offset:56320
	global_load_lds_dwordx4 v132, s[12:13] offset:128
	s_barrier
	s_waitcnt lgkmcnt(0)
	s_setprio 1
	v_mfma_f32_16x16x32_bf16 v[60:63], v[146:149], v[174:177], v[60:63]
	v_mfma_f32_16x16x32_bf16 v[56:59], v[154:157], v[174:177], v[56:59]
	v_mfma_f32_16x16x32_bf16 v[44:47], v[146:149], v[188:191], v[44:47]
	v_mfma_f32_16x16x32_bf16 v[40:43], v[154:157], v[188:191], v[40:43]
	v_mfma_f32_16x16x32_bf16 v[28:31], v[146:149], v[198:201], v[28:31]
	v_mfma_f32_16x16x32_bf16 v[24:27], v[154:157], v[198:201], v[24:27]
	v_mfma_f32_16x16x32_bf16 v[12:15], v[146:149], v[206:209], v[12:15]
	v_mfma_f32_16x16x32_bf16 v[8:11], v[154:157], v[206:209], v[8:11]
	v_mfma_f32_16x16x32_bf16 v[60:63], v[150:153], v[178:181], v[60:63]
	v_mfma_f32_16x16x32_bf16 v[56:59], v[170:173], v[178:181], v[56:59]
	v_mfma_f32_16x16x32_bf16 v[44:47], v[150:153], v[194:197], v[44:47]
	v_mfma_f32_16x16x32_bf16 v[40:43], v[170:173], v[194:197], v[40:43]
	v_mfma_f32_16x16x32_bf16 v[28:31], v[150:153], v[202:205], v[28:31]
	v_mfma_f32_16x16x32_bf16 v[24:27], v[170:173], v[202:205], v[24:27]
	v_mfma_f32_16x16x32_bf16 v[12:15], v[150:153], v[210:213], v[12:15]
	v_mfma_f32_16x16x32_bf16 v[8:11], v[170:173], v[210:213], v[8:11]
	s_setprio 0
	s_barrier
	s_add_u32 s0, s10, 0x80080
	s_addc_u32 s1, s11, 0
	s_add_i32 s4, s5, s74
	s_mov_b32 m0, s4
	s_nop 0
	global_load_lds_dwordx4 v130, s[0:1]
	v_lshl_add_u64 v[146:147], s[0:1], 0, v[134:135]
	s_add_i32 m0, s4, 0x2000
	s_nop 0
	global_load_lds_dwordx4 v134, s[0:1]
	s_waitcnt vmcnt(6)
	s_barrier
	s_setprio 1
	v_mfma_f32_16x16x32_bf16 v[52:55], v[214:217], v[174:177], v[52:55]
	v_mfma_f32_16x16x32_bf16 v[48:51], v[222:225], v[174:177], v[48:51]
	v_mfma_f32_16x16x32_bf16 v[36:39], v[214:217], v[188:191], v[36:39]
	v_mfma_f32_16x16x32_bf16 v[32:35], v[222:225], v[188:191], v[32:35]
	v_mfma_f32_16x16x32_bf16 v[20:23], v[214:217], v[198:201], v[20:23]
	v_mfma_f32_16x16x32_bf16 v[16:19], v[222:225], v[198:201], v[16:19]
	v_mfma_f32_16x16x32_bf16 v[4:7], v[214:217], v[206:209], v[4:7]
	v_mfma_f32_16x16x32_bf16 v[0:3], v[222:225], v[206:209], v[0:3]
	v_mfma_f32_16x16x32_bf16 v[52:55], v[218:221], v[178:181], v[52:55]
	v_mfma_f32_16x16x32_bf16 v[48:51], v[226:229], v[178:181], v[48:51]
	v_mfma_f32_16x16x32_bf16 v[36:39], v[218:221], v[194:197], v[36:39]
	v_mfma_f32_16x16x32_bf16 v[32:35], v[226:229], v[194:197], v[32:35]
	v_mfma_f32_16x16x32_bf16 v[20:23], v[218:221], v[202:205], v[20:23]
	v_mfma_f32_16x16x32_bf16 v[16:19], v[226:229], v[202:205], v[16:19]
	v_mfma_f32_16x16x32_bf16 v[4:7], v[218:221], v[210:213], v[4:7]
	v_mfma_f32_16x16x32_bf16 v[0:3], v[226:229], v[210:213], v[0:3]
	s_setprio 0
	s_add_i32 s35, s35, 2
	s_add_u32 s8, s8, 0x100
	s_addc_u32 s9, s9, 0
	s_add_u32 s28, s28, 0x100
	s_addc_u32 s34, s34, 0
	s_cmp_gt_u32 s35, 29
	s_barrier
	s_cbranch_scc0 .LBB0_527
